# hand-scheduled SWIGLU/GLU/RET-gate epilogues with 16-byte stores via v_permlane16_swap
# speedup vs baseline: 1.0317x; 1.0085x over previous
.LBB0_899:
	s_and_b64 vcc, exec, s[2:3]
	s_cbranch_vccz .LBB0_901
	s_branch .Lretg_fast
	v_readlane_b32 s2, v253, 36
	v_add_u32_e32 v132, 0xfffffc00, v162
	v_ashrrev_i32_e32 v133, 31, v132
	v_mov_b32_e32 v0, s2
	ds_read_b64 v[130:131], v0
	v_ashrrev_i32_e32 v161, 31, v160
	v_mul_f32_e32 v0, 0xbfb8aa3b, v126
	s_waitcnt lgkmcnt(0)
	v_lshl_add_u64 v[130:131], v[132:133], 1, v[130:131]
	v_lshlrev_b64 v[132:133], 12, v[160:161]
	v_lshl_add_u64 v[130:131], v[130:131], 0, v[132:133]
	v_exp_f32_e32 v132, v0
	v_mul_f32_e32 v0, 0xbfb8aa3b, v127
	v_exp_f32_e32 v133, v0
	s_nop 0
	v_pk_add_f32 v[132:133], v[132:133], 1.0 op_sel_hi:[1,0]
	s_nop 0
	v_rcp_f32_e32 v134, v133
	s_nop 0
	v_mul_f32_e32 v0, v127, v134
	v_rcp_f32_e32 v134, v132
	s_nop 0
	v_mul_f32_e32 v134, v126, v134
	v_mul_f32_e32 v132, 0xbfb8aa3b, v128
	v_mul_f32_e32 v133, 0xbfb8aa3b, v129
	v_exp_f32_e32 v132, v132
	v_exp_f32_e32 v133, v133
	s_nop 0
	v_pk_add_f32 v[132:133], v[132:133], 1.0 op_sel_hi:[1,0]
	s_nop 0
	v_rcp_f32_e32 v136, v133
	s_nop 0
	v_mul_f32_e32 v133, v129, v136
	v_rcp_f32_e32 v136, v132
	s_nop 0
	v_mul_f32_e32 v135, v128, v136
	v_cvt_pk_bf16_f32 v132, v134, v0
	v_cvt_pk_bf16_f32 v133, v135, v133
	v_mul_f32_e32 v0, 0xbfb8aa3b, v118
	global_store_dwordx2 v[130:131], v[132:133], off
	v_exp_f32_e32 v132, v0
	v_mul_f32_e32 v0, 0xbfb8aa3b, v119
	v_exp_f32_e32 v133, v0
	s_nop 0
	v_pk_add_f32 v[132:133], v[132:133], 1.0 op_sel_hi:[1,0]
	s_nop 0
	v_rcp_f32_e32 v134, v133
	s_nop 0
	v_mul_f32_e32 v0, v119, v134
	v_rcp_f32_e32 v134, v132
	s_nop 0
	v_mul_f32_e32 v134, v118, v134
	v_mul_f32_e32 v132, 0xbfb8aa3b, v120
	v_mul_f32_e32 v133, 0xbfb8aa3b, v121
	v_exp_f32_e32 v132, v132
	v_exp_f32_e32 v133, v133
	s_nop 0
	v_pk_add_f32 v[132:133], v[132:133], 1.0 op_sel_hi:[1,0]
	s_nop 0
	v_rcp_f32_e32 v136, v133
	s_nop 0
	v_mul_f32_e32 v133, v121, v136
	v_rcp_f32_e32 v136, v132
	s_nop 0
	v_mul_f32_e32 v135, v120, v136
	v_cvt_pk_bf16_f32 v132, v134, v0
	v_cvt_pk_bf16_f32 v133, v135, v133
	v_mul_f32_e32 v0, 0xbfb8aa3b, v122
	global_store_dwordx2 v[130:131], v[132:133], off offset:32
	v_exp_f32_e32 v132, v0
	v_mul_f32_e32 v0, 0xbfb8aa3b, v123
	v_exp_f32_e32 v133, v0
	s_nop 0
	v_pk_add_f32 v[132:133], v[132:133], 1.0 op_sel_hi:[1,0]
	s_nop 0
	v_rcp_f32_e32 v134, v133
	s_nop 0
	v_mul_f32_e32 v0, v123, v134
	v_rcp_f32_e32 v134, v132
	s_nop 0
	v_mul_f32_e32 v134, v122, v134
	v_mul_f32_e32 v132, 0xbfb8aa3b, v124
	v_mul_f32_e32 v133, 0xbfb8aa3b, v125
	v_exp_f32_e32 v132, v132
	v_exp_f32_e32 v133, v133
	s_nop 0
	v_pk_add_f32 v[132:133], v[132:133], 1.0 op_sel_hi:[1,0]
	s_nop 0
	v_rcp_f32_e32 v136, v133
	s_nop 0
	v_mul_f32_e32 v133, v125, v136
	v_rcp_f32_e32 v136, v132
	s_nop 0
	v_mul_f32_e32 v135, v124, v136
	v_cvt_pk_bf16_f32 v132, v134, v0
	v_cvt_pk_bf16_f32 v133, v135, v133
	v_mul_f32_e32 v0, 0xbfb8aa3b, v114
	global_store_dwordx2 v[130:131], v[132:133], off offset:256
	v_exp_f32_e32 v132, v0
	v_mul_f32_e32 v0, 0xbfb8aa3b, v115
	v_exp_f32_e32 v133, v0
	s_nop 0
	v_pk_add_f32 v[132:133], v[132:133], 1.0 op_sel_hi:[1,0]
	s_nop 0
	v_rcp_f32_e32 v134, v133
	s_nop 0
	v_mul_f32_e32 v0, v115, v134
	v_rcp_f32_e32 v134, v132
	s_nop 0
	v_mul_f32_e32 v134, v114, v134
	v_mul_f32_e32 v132, 0xbfb8aa3b, v116
	v_mul_f32_e32 v133, 0xbfb8aa3b, v117
	v_exp_f32_e32 v132, v132
	v_exp_f32_e32 v133, v133
	s_nop 0
	v_pk_add_f32 v[132:133], v[132:133], 1.0 op_sel_hi:[1,0]
	s_nop 0
	v_rcp_f32_e32 v136, v133
	s_nop 0
	v_mul_f32_e32 v133, v117, v136
	v_rcp_f32_e32 v136, v132
	s_mov_b64 s[2:3], 0x10000
	v_mul_f32_e32 v135, v116, v136
	v_cvt_pk_bf16_f32 v132, v134, v0
	v_mul_f32_e32 v0, 0xbfb8aa3b, v110
	v_exp_f32_e32 v134, v0
	v_mul_f32_e32 v0, 0xbfb8aa3b, v111
	v_cvt_pk_bf16_f32 v133, v135, v133
	v_exp_f32_e32 v135, v0
	global_store_dwordx2 v[130:131], v[132:133], off offset:288
	v_lshl_add_u64 v[132:133], v[130:131], 0, s[2:3]
	v_pk_add_f32 v[134:135], v[134:135], 1.0 op_sel_hi:[1,0]
	s_nop 0
	v_rcp_f32_e32 v136, v135
	s_nop 0
	v_mul_f32_e32 v0, v111, v136
	v_rcp_f32_e32 v136, v134
	s_nop 0
	v_mul_f32_e32 v136, v110, v136
	v_mul_f32_e32 v134, 0xbfb8aa3b, v112
	v_mul_f32_e32 v135, 0xbfb8aa3b, v113
	v_exp_f32_e32 v134, v134
	v_exp_f32_e32 v135, v135
	s_nop 0
	v_pk_add_f32 v[134:135], v[134:135], 1.0 op_sel_hi:[1,0]
	s_nop 0
	v_rcp_f32_e32 v138, v135
	s_nop 0
	v_mul_f32_e32 v135, v113, v138
	v_rcp_f32_e32 v138, v134
	s_mov_b32 s2, 0x10000
	v_mul_f32_e32 v137, v112, v138
	v_cvt_pk_bf16_f32 v134, v136, v0
	v_add_co_u32_e32 v136, vcc, s2, v130
	v_cvt_pk_bf16_f32 v135, v137, v135
	s_nop 0
	v_addc_co_u32_e32 v137, vcc, 0, v131, vcc
	v_mul_f32_e32 v0, 0xbfb8aa3b, v102
	global_store_dwordx2 v[136:137], v[134:135], off
	v_exp_f32_e32 v134, v0
	v_mul_f32_e32 v0, 0xbfb8aa3b, v103
	v_exp_f32_e32 v135, v0
	s_nop 0
	v_pk_add_f32 v[134:135], v[134:135], 1.0 op_sel_hi:[1,0]
	s_nop 0
	v_rcp_f32_e32 v136, v135
	s_nop 0
	v_mul_f32_e32 v0, v103, v136
	v_rcp_f32_e32 v136, v134
	s_nop 0
	v_mul_f32_e32 v136, v102, v136
	v_mul_f32_e32 v134, 0xbfb8aa3b, v104
	v_mul_f32_e32 v135, 0xbfb8aa3b, v105
	v_exp_f32_e32 v134, v134
	v_exp_f32_e32 v135, v135
	s_nop 0
	v_pk_add_f32 v[134:135], v[134:135], 1.0 op_sel_hi:[1,0]
	s_nop 0
	v_rcp_f32_e32 v138, v135
	s_nop 0
	v_mul_f32_e32 v135, v105, v138
	v_rcp_f32_e32 v138, v134
	s_nop 0
	v_mul_f32_e32 v137, v104, v138
	v_cvt_pk_bf16_f32 v134, v136, v0
	v_cvt_pk_bf16_f32 v135, v137, v135
	v_mul_f32_e32 v0, 0xbfb8aa3b, v106
	global_store_dwordx2 v[132:133], v[134:135], off offset:32
	v_exp_f32_e32 v134, v0
	v_mul_f32_e32 v0, 0xbfb8aa3b, v107
	v_exp_f32_e32 v135, v0
	s_nop 0
	v_pk_add_f32 v[134:135], v[134:135], 1.0 op_sel_hi:[1,0]
	s_nop 0
	v_rcp_f32_e32 v136, v135
	s_nop 0
	v_mul_f32_e32 v0, v107, v136
	v_rcp_f32_e32 v136, v134
	s_nop 0
	v_mul_f32_e32 v136, v106, v136
	v_mul_f32_e32 v134, 0xbfb8aa3b, v108
	v_mul_f32_e32 v135, 0xbfb8aa3b, v109
	v_exp_f32_e32 v134, v134
	v_exp_f32_e32 v135, v135
	s_nop 0
	v_pk_add_f32 v[134:135], v[134:135], 1.0 op_sel_hi:[1,0]
	s_nop 0
	v_rcp_f32_e32 v138, v135
	s_nop 0
	v_mul_f32_e32 v135, v109, v138
	v_rcp_f32_e32 v138, v134
	s_nop 0
	v_mul_f32_e32 v137, v108, v138
	v_cvt_pk_bf16_f32 v134, v136, v0
	v_cvt_pk_bf16_f32 v135, v137, v135
	v_mul_f32_e32 v0, 0xbfb8aa3b, v98
	global_store_dwordx2 v[132:133], v[134:135], off offset:256
	v_exp_f32_e32 v134, v0
	v_mul_f32_e32 v0, 0xbfb8aa3b, v99
	v_exp_f32_e32 v135, v0
	s_nop 0
	v_pk_add_f32 v[134:135], v[134:135], 1.0 op_sel_hi:[1,0]
	s_nop 0
	v_rcp_f32_e32 v136, v135
	s_nop 0
	v_mul_f32_e32 v0, v99, v136
	v_rcp_f32_e32 v136, v134
	s_nop 0
	v_mul_f32_e32 v136, v98, v136
	v_mul_f32_e32 v134, 0xbfb8aa3b, v100
	v_mul_f32_e32 v135, 0xbfb8aa3b, v101
	v_exp_f32_e32 v134, v134
	v_exp_f32_e32 v135, v135
	s_nop 0
	v_pk_add_f32 v[134:135], v[134:135], 1.0 op_sel_hi:[1,0]
	s_nop 0
	v_rcp_f32_e32 v138, v135
	s_nop 0
	v_mul_f32_e32 v135, v101, v138
	v_rcp_f32_e32 v138, v134
	s_mov_b64 s[2:3], 0x20000
	v_mul_f32_e32 v137, v100, v138
	v_cvt_pk_bf16_f32 v134, v136, v0
	v_cvt_pk_bf16_f32 v135, v137, v135
	v_mul_f32_e32 v0, 0xbfb8aa3b, v94
	global_store_dwordx2 v[132:133], v[134:135], off offset:288
	v_exp_f32_e32 v134, v0
	v_mul_f32_e32 v0, 0xbfb8aa3b, v95
	v_exp_f32_e32 v135, v0
	v_lshl_add_u64 v[132:133], v[130:131], 0, s[2:3]
	v_pk_add_f32 v[134:135], v[134:135], 1.0 op_sel_hi:[1,0]
	s_nop 0
	v_rcp_f32_e32 v136, v135
	s_nop 0
	v_mul_f32_e32 v0, v95, v136
	v_rcp_f32_e32 v136, v134
	s_nop 0
	v_mul_f32_e32 v136, v94, v136
	v_mul_f32_e32 v134, 0xbfb8aa3b, v96
	v_mul_f32_e32 v135, 0xbfb8aa3b, v97
	v_exp_f32_e32 v134, v134
	v_exp_f32_e32 v135, v135
	s_nop 0
	v_pk_add_f32 v[134:135], v[134:135], 1.0 op_sel_hi:[1,0]
	s_nop 0
	v_rcp_f32_e32 v138, v135
	s_nop 0
	v_mul_f32_e32 v135, v97, v138
	v_rcp_f32_e32 v138, v134
	s_mov_b32 s2, 0x20000
	v_mul_f32_e32 v137, v96, v138
	v_cvt_pk_bf16_f32 v134, v136, v0
	v_add_co_u32_e32 v136, vcc, s2, v130
	v_cvt_pk_bf16_f32 v135, v137, v135
	s_nop 0
	v_addc_co_u32_e32 v137, vcc, 0, v131, vcc
	v_mul_f32_e32 v0, 0xbfb8aa3b, v86
	global_store_dwordx2 v[136:137], v[134:135], off
	v_exp_f32_e32 v134, v0
	v_mul_f32_e32 v0, 0xbfb8aa3b, v87
	v_exp_f32_e32 v135, v0
	s_nop 0
	v_pk_add_f32 v[134:135], v[134:135], 1.0 op_sel_hi:[1,0]
	s_nop 0
	v_rcp_f32_e32 v136, v135
	s_nop 0
	v_mul_f32_e32 v0, v87, v136
	v_rcp_f32_e32 v136, v134
	s_nop 0
	v_mul_f32_e32 v136, v86, v136
	v_mul_f32_e32 v134, 0xbfb8aa3b, v88
	v_mul_f32_e32 v135, 0xbfb8aa3b, v89
	v_exp_f32_e32 v134, v134
	v_exp_f32_e32 v135, v135
	s_nop 0
	v_pk_add_f32 v[134:135], v[134:135], 1.0 op_sel_hi:[1,0]
	s_nop 0
	v_rcp_f32_e32 v138, v135
	s_nop 0
	v_mul_f32_e32 v135, v89, v138
	v_rcp_f32_e32 v138, v134
	s_nop 0
	v_mul_f32_e32 v137, v88, v138
	v_cvt_pk_bf16_f32 v134, v136, v0
	v_cvt_pk_bf16_f32 v135, v137, v135
	v_mul_f32_e32 v0, 0xbfb8aa3b, v90
	global_store_dwordx2 v[132:133], v[134:135], off offset:32
	v_exp_f32_e32 v134, v0
	v_mul_f32_e32 v0, 0xbfb8aa3b, v91
	v_exp_f32_e32 v135, v0
	s_nop 0
	v_pk_add_f32 v[134:135], v[134:135], 1.0 op_sel_hi:[1,0]
	s_nop 0
	v_rcp_f32_e32 v136, v135
	s_nop 0
	v_mul_f32_e32 v0, v91, v136
	v_rcp_f32_e32 v136, v134
	s_nop 0
	v_mul_f32_e32 v136, v90, v136
	v_mul_f32_e32 v134, 0xbfb8aa3b, v92
	v_mul_f32_e32 v135, 0xbfb8aa3b, v93
	v_exp_f32_e32 v134, v134
	v_exp_f32_e32 v135, v135
	s_nop 0
	v_pk_add_f32 v[134:135], v[134:135], 1.0 op_sel_hi:[1,0]
	s_nop 0
	v_rcp_f32_e32 v138, v135
	s_nop 0
	v_mul_f32_e32 v135, v93, v138
	v_rcp_f32_e32 v138, v134
	s_nop 0
	v_mul_f32_e32 v137, v92, v138
	v_cvt_pk_bf16_f32 v134, v136, v0
	v_cvt_pk_bf16_f32 v135, v137, v135
	v_mul_f32_e32 v0, 0xbfb8aa3b, v82
	global_store_dwordx2 v[132:133], v[134:135], off offset:256
	v_exp_f32_e32 v134, v0
	v_mul_f32_e32 v0, 0xbfb8aa3b, v83
	v_exp_f32_e32 v135, v0
	s_nop 0
	v_pk_add_f32 v[134:135], v[134:135], 1.0 op_sel_hi:[1,0]
	s_nop 0
	v_rcp_f32_e32 v136, v135
	s_nop 0
	v_mul_f32_e32 v0, v83, v136
	v_rcp_f32_e32 v136, v134
	s_nop 0
	v_mul_f32_e32 v136, v82, v136
	v_mul_f32_e32 v134, 0xbfb8aa3b, v84
	v_mul_f32_e32 v135, 0xbfb8aa3b, v85
	v_exp_f32_e32 v134, v134
	v_exp_f32_e32 v135, v135
	s_nop 0
	v_pk_add_f32 v[134:135], v[134:135], 1.0 op_sel_hi:[1,0]
	s_nop 0
	v_rcp_f32_e32 v138, v135
	s_nop 0
	v_mul_f32_e32 v135, v85, v138
	v_rcp_f32_e32 v138, v134
	s_mov_b64 s[2:3], 0x30000
	v_mul_f32_e32 v137, v84, v138
	v_cvt_pk_bf16_f32 v134, v136, v0
	v_cvt_pk_bf16_f32 v135, v137, v135
	v_mul_f32_e32 v0, 0xbfb8aa3b, v78
	global_store_dwordx2 v[132:133], v[134:135], off offset:288
	v_exp_f32_e32 v134, v0
	v_mul_f32_e32 v0, 0xbfb8aa3b, v79
	v_exp_f32_e32 v135, v0
	v_lshl_add_u64 v[132:133], v[130:131], 0, s[2:3]
	v_pk_add_f32 v[134:135], v[134:135], 1.0 op_sel_hi:[1,0]
	s_nop 0
	v_rcp_f32_e32 v136, v135
	s_nop 0
	v_mul_f32_e32 v0, v79, v136
	v_rcp_f32_e32 v136, v134
	s_nop 0
	v_mul_f32_e32 v136, v78, v136
	v_mul_f32_e32 v134, 0xbfb8aa3b, v80
	v_mul_f32_e32 v135, 0xbfb8aa3b, v81
	v_exp_f32_e32 v134, v134
	v_exp_f32_e32 v135, v135
	s_nop 0
	v_pk_add_f32 v[134:135], v[134:135], 1.0 op_sel_hi:[1,0]
	s_nop 0
	v_rcp_f32_e32 v138, v135
	s_nop 0
	v_mul_f32_e32 v135, v81, v138
	v_rcp_f32_e32 v138, v134
	s_mov_b32 s2, 0x30000
	v_mul_f32_e32 v137, v80, v138
	v_cvt_pk_bf16_f32 v134, v136, v0
	v_add_co_u32_e32 v136, vcc, s2, v130
	v_cvt_pk_bf16_f32 v135, v137, v135
	s_nop 0
	v_addc_co_u32_e32 v137, vcc, 0, v131, vcc
	v_mul_f32_e32 v0, 0xbfb8aa3b, v70
	global_store_dwordx2 v[136:137], v[134:135], off
	v_exp_f32_e32 v134, v0
	v_mul_f32_e32 v0, 0xbfb8aa3b, v71
	v_exp_f32_e32 v135, v0
	s_nop 0
	v_pk_add_f32 v[134:135], v[134:135], 1.0 op_sel_hi:[1,0]
	s_nop 0
	v_rcp_f32_e32 v136, v135
	s_nop 0
	v_mul_f32_e32 v0, v71, v136
	v_rcp_f32_e32 v136, v134
	s_nop 0
	v_mul_f32_e32 v136, v70, v136
	v_mul_f32_e32 v134, 0xbfb8aa3b, v72
	v_mul_f32_e32 v135, 0xbfb8aa3b, v73
	v_exp_f32_e32 v134, v134
	v_exp_f32_e32 v135, v135
	s_nop 0
	v_pk_add_f32 v[134:135], v[134:135], 1.0 op_sel_hi:[1,0]
	s_nop 0
	v_rcp_f32_e32 v138, v135
	s_nop 0
	v_mul_f32_e32 v135, v73, v138
	v_rcp_f32_e32 v138, v134
	s_nop 0
	v_mul_f32_e32 v137, v72, v138
	v_cvt_pk_bf16_f32 v134, v136, v0
	v_cvt_pk_bf16_f32 v135, v137, v135
	v_mul_f32_e32 v0, 0xbfb8aa3b, v74
	global_store_dwordx2 v[132:133], v[134:135], off offset:32
	v_exp_f32_e32 v134, v0
	v_mul_f32_e32 v0, 0xbfb8aa3b, v75
	v_exp_f32_e32 v135, v0
	s_nop 0
	v_pk_add_f32 v[134:135], v[134:135], 1.0 op_sel_hi:[1,0]
	s_nop 0
	v_rcp_f32_e32 v136, v135
	s_nop 0
	v_mul_f32_e32 v0, v75, v136
	v_rcp_f32_e32 v136, v134
	s_nop 0
	v_mul_f32_e32 v136, v74, v136
	v_mul_f32_e32 v134, 0xbfb8aa3b, v76
	v_mul_f32_e32 v135, 0xbfb8aa3b, v77
	v_exp_f32_e32 v134, v134
	v_exp_f32_e32 v135, v135
	s_nop 0
	v_pk_add_f32 v[134:135], v[134:135], 1.0 op_sel_hi:[1,0]
	s_nop 0
	v_rcp_f32_e32 v138, v135
	s_nop 0
	v_mul_f32_e32 v135, v77, v138
	v_rcp_f32_e32 v138, v134
	s_nop 0
	v_mul_f32_e32 v137, v76, v138
	v_cvt_pk_bf16_f32 v134, v136, v0
	v_cvt_pk_bf16_f32 v135, v137, v135
	v_mul_f32_e32 v0, 0xbfb8aa3b, v66
	global_store_dwordx2 v[132:133], v[134:135], off offset:256
	v_exp_f32_e32 v134, v0
	v_mul_f32_e32 v0, 0xbfb8aa3b, v67
	v_exp_f32_e32 v135, v0
	s_nop 0
	v_pk_add_f32 v[134:135], v[134:135], 1.0 op_sel_hi:[1,0]
	s_nop 0
	v_rcp_f32_e32 v136, v135
	s_nop 0
	v_mul_f32_e32 v0, v67, v136
	v_rcp_f32_e32 v136, v134
	s_nop 0
	v_mul_f32_e32 v136, v66, v136
	v_mul_f32_e32 v134, 0xbfb8aa3b, v68
	v_mul_f32_e32 v135, 0xbfb8aa3b, v69
	v_exp_f32_e32 v134, v134
	v_exp_f32_e32 v135, v135
	s_nop 0
	v_pk_add_f32 v[134:135], v[134:135], 1.0 op_sel_hi:[1,0]
	s_nop 0
	v_rcp_f32_e32 v138, v135
	s_nop 0
	v_mul_f32_e32 v135, v69, v138
	v_rcp_f32_e32 v138, v134
	s_mov_b64 s[2:3], 0x80000
	v_mul_f32_e32 v137, v68, v138
	v_cvt_pk_bf16_f32 v134, v136, v0
	v_cvt_pk_bf16_f32 v135, v137, v135
	v_mul_f32_e32 v0, 0xbfb8aa3b, v62
	global_store_dwordx2 v[132:133], v[134:135], off offset:288
	v_exp_f32_e32 v134, v0
	v_mul_f32_e32 v0, 0xbfb8aa3b, v63
	v_exp_f32_e32 v135, v0
	v_lshl_add_u64 v[132:133], v[130:131], 0, s[2:3]
	v_pk_add_f32 v[134:135], v[134:135], 1.0 op_sel_hi:[1,0]
	s_nop 0
	v_rcp_f32_e32 v136, v135
	s_nop 0
	v_mul_f32_e32 v0, v63, v136
	v_rcp_f32_e32 v136, v134
	s_nop 0
	v_mul_f32_e32 v136, v62, v136
	v_mul_f32_e32 v134, 0xbfb8aa3b, v64
	v_mul_f32_e32 v135, 0xbfb8aa3b, v65
	v_exp_f32_e32 v134, v134
	v_exp_f32_e32 v135, v135
	s_nop 0
	v_pk_add_f32 v[134:135], v[134:135], 1.0 op_sel_hi:[1,0]
	s_nop 0
	v_rcp_f32_e32 v138, v135
	s_nop 0
	v_mul_f32_e32 v135, v65, v138
	v_rcp_f32_e32 v138, v134
	s_mov_b32 s2, 0x80000
	v_mul_f32_e32 v137, v64, v138
	v_cvt_pk_bf16_f32 v134, v136, v0
	v_add_co_u32_e32 v136, vcc, s2, v130
	v_cvt_pk_bf16_f32 v135, v137, v135
	s_nop 0
	v_addc_co_u32_e32 v137, vcc, 0, v131, vcc
	v_mul_f32_e32 v0, 0xbfb8aa3b, v54
	global_store_dwordx2 v[136:137], v[134:135], off
	v_exp_f32_e32 v134, v0
	v_mul_f32_e32 v0, 0xbfb8aa3b, v55
	v_exp_f32_e32 v135, v0
	s_nop 0
	v_pk_add_f32 v[134:135], v[134:135], 1.0 op_sel_hi:[1,0]
	s_nop 0
	v_rcp_f32_e32 v136, v135
	s_nop 0
	v_mul_f32_e32 v0, v55, v136
	v_rcp_f32_e32 v136, v134
	s_nop 0
	v_mul_f32_e32 v136, v54, v136
	v_mul_f32_e32 v134, 0xbfb8aa3b, v56
	v_mul_f32_e32 v135, 0xbfb8aa3b, v57
	v_exp_f32_e32 v134, v134
	v_exp_f32_e32 v135, v135
	s_nop 0
	v_pk_add_f32 v[134:135], v[134:135], 1.0 op_sel_hi:[1,0]
	s_nop 0
	v_rcp_f32_e32 v138, v135
	s_nop 0
	v_mul_f32_e32 v135, v57, v138
	v_rcp_f32_e32 v138, v134
	s_nop 0
	v_mul_f32_e32 v137, v56, v138
	v_cvt_pk_bf16_f32 v134, v136, v0
	v_cvt_pk_bf16_f32 v135, v137, v135
	v_mul_f32_e32 v0, 0xbfb8aa3b, v58
	global_store_dwordx2 v[132:133], v[134:135], off offset:32
	v_exp_f32_e32 v134, v0
	v_mul_f32_e32 v0, 0xbfb8aa3b, v59
	v_exp_f32_e32 v135, v0
	s_nop 0
	v_pk_add_f32 v[134:135], v[134:135], 1.0 op_sel_hi:[1,0]
	s_nop 0
	v_rcp_f32_e32 v136, v135
	s_nop 0
	v_mul_f32_e32 v0, v59, v136
	v_rcp_f32_e32 v136, v134
	s_nop 0
	v_mul_f32_e32 v136, v58, v136
	v_mul_f32_e32 v134, 0xbfb8aa3b, v60
	v_mul_f32_e32 v135, 0xbfb8aa3b, v61
	v_exp_f32_e32 v134, v134
	v_exp_f32_e32 v135, v135
	s_nop 0
	v_pk_add_f32 v[134:135], v[134:135], 1.0 op_sel_hi:[1,0]
	s_nop 0
	v_rcp_f32_e32 v138, v135
	s_nop 0
	v_mul_f32_e32 v135, v61, v138
	v_rcp_f32_e32 v138, v134
	s_nop 0
	v_mul_f32_e32 v137, v60, v138
	v_cvt_pk_bf16_f32 v134, v136, v0
	v_cvt_pk_bf16_f32 v135, v137, v135
	v_mul_f32_e32 v0, 0xbfb8aa3b, v50
	global_store_dwordx2 v[132:133], v[134:135], off offset:256
	v_exp_f32_e32 v134, v0
	v_mul_f32_e32 v0, 0xbfb8aa3b, v51
	v_exp_f32_e32 v135, v0
	s_nop 0
	v_pk_add_f32 v[134:135], v[134:135], 1.0 op_sel_hi:[1,0]
	s_nop 0
	v_rcp_f32_e32 v136, v135
	s_nop 0
	v_mul_f32_e32 v0, v51, v136
	v_rcp_f32_e32 v136, v134
	s_nop 0
	v_mul_f32_e32 v136, v50, v136
	v_mul_f32_e32 v134, 0xbfb8aa3b, v52
	v_mul_f32_e32 v135, 0xbfb8aa3b, v53
	v_exp_f32_e32 v134, v134
	v_exp_f32_e32 v135, v135
	s_nop 0
	v_pk_add_f32 v[134:135], v[134:135], 1.0 op_sel_hi:[1,0]
	s_nop 0
	v_rcp_f32_e32 v138, v135
	s_nop 0
	v_mul_f32_e32 v135, v53, v138
	v_rcp_f32_e32 v138, v134
	s_mov_b64 s[2:3], 0x90000
	v_mul_f32_e32 v137, v52, v138
	v_cvt_pk_bf16_f32 v134, v136, v0
	v_cvt_pk_bf16_f32 v135, v137, v135
	v_mul_f32_e32 v0, 0xbfb8aa3b, v46
	global_store_dwordx2 v[132:133], v[134:135], off offset:288
	v_exp_f32_e32 v134, v0
	v_mul_f32_e32 v0, 0xbfb8aa3b, v47
	v_exp_f32_e32 v135, v0
	v_lshl_add_u64 v[132:133], v[130:131], 0, s[2:3]
	v_pk_add_f32 v[134:135], v[134:135], 1.0 op_sel_hi:[1,0]
	s_nop 0
	v_rcp_f32_e32 v136, v135
	s_nop 0
	v_mul_f32_e32 v0, v47, v136
	v_rcp_f32_e32 v136, v134
	s_nop 0
	v_mul_f32_e32 v136, v46, v136
	v_mul_f32_e32 v134, 0xbfb8aa3b, v48
	v_mul_f32_e32 v135, 0xbfb8aa3b, v49
	v_exp_f32_e32 v134, v134
	v_exp_f32_e32 v135, v135
	s_nop 0
	v_pk_add_f32 v[134:135], v[134:135], 1.0 op_sel_hi:[1,0]
	s_nop 0
	v_rcp_f32_e32 v138, v135
	s_nop 0
	v_mul_f32_e32 v135, v49, v138
	v_rcp_f32_e32 v138, v134
	s_mov_b32 s2, 0x90000
	v_mul_f32_e32 v137, v48, v138
	v_cvt_pk_bf16_f32 v134, v136, v0
	v_add_co_u32_e32 v136, vcc, s2, v130
	v_cvt_pk_bf16_f32 v135, v137, v135
	s_nop 0
	v_addc_co_u32_e32 v137, vcc, 0, v131, vcc
	v_mul_f32_e32 v0, 0xbfb8aa3b, v38
	global_store_dwordx2 v[136:137], v[134:135], off
	v_exp_f32_e32 v134, v0
	v_mul_f32_e32 v0, 0xbfb8aa3b, v39
	v_exp_f32_e32 v135, v0
	s_nop 0
	v_pk_add_f32 v[134:135], v[134:135], 1.0 op_sel_hi:[1,0]
	s_nop 0
	v_rcp_f32_e32 v136, v135
	s_nop 0
	v_mul_f32_e32 v0, v39, v136
	v_rcp_f32_e32 v136, v134
	s_nop 0
	v_mul_f32_e32 v136, v38, v136
	v_mul_f32_e32 v134, 0xbfb8aa3b, v40
	v_mul_f32_e32 v135, 0xbfb8aa3b, v41
	v_exp_f32_e32 v134, v134
	v_exp_f32_e32 v135, v135
	s_nop 0
	v_pk_add_f32 v[134:135], v[134:135], 1.0 op_sel_hi:[1,0]
	s_nop 0
	v_rcp_f32_e32 v138, v135
	s_nop 0
	v_mul_f32_e32 v135, v41, v138
	v_rcp_f32_e32 v138, v134
	s_nop 0
	v_mul_f32_e32 v137, v40, v138
	v_cvt_pk_bf16_f32 v134, v136, v0
	v_cvt_pk_bf16_f32 v135, v137, v135
	v_mul_f32_e32 v0, 0xbfb8aa3b, v42
	global_store_dwordx2 v[132:133], v[134:135], off offset:32
	v_exp_f32_e32 v134, v0
	v_mul_f32_e32 v0, 0xbfb8aa3b, v43
	v_exp_f32_e32 v135, v0
	s_nop 0
	v_pk_add_f32 v[134:135], v[134:135], 1.0 op_sel_hi:[1,0]
	s_nop 0
	v_rcp_f32_e32 v136, v135
	s_nop 0
	v_mul_f32_e32 v0, v43, v136
	v_rcp_f32_e32 v136, v134
	s_nop 0
	v_mul_f32_e32 v136, v42, v136
	v_mul_f32_e32 v134, 0xbfb8aa3b, v44
	v_mul_f32_e32 v135, 0xbfb8aa3b, v45
	v_exp_f32_e32 v134, v134
	v_exp_f32_e32 v135, v135
	s_nop 0
	v_pk_add_f32 v[134:135], v[134:135], 1.0 op_sel_hi:[1,0]
	s_nop 0
	v_rcp_f32_e32 v138, v135
	s_nop 0
	v_mul_f32_e32 v135, v45, v138
	v_rcp_f32_e32 v138, v134
	s_nop 0
	v_mul_f32_e32 v137, v44, v138
	v_cvt_pk_bf16_f32 v134, v136, v0
	v_cvt_pk_bf16_f32 v135, v137, v135
	v_mul_f32_e32 v0, 0xbfb8aa3b, v34
	global_store_dwordx2 v[132:133], v[134:135], off offset:256
	v_exp_f32_e32 v134, v0
	v_mul_f32_e32 v0, 0xbfb8aa3b, v35
	v_exp_f32_e32 v135, v0
	s_nop 0
	v_pk_add_f32 v[134:135], v[134:135], 1.0 op_sel_hi:[1,0]
	s_nop 0
	v_rcp_f32_e32 v136, v135
	s_nop 0
	v_mul_f32_e32 v0, v35, v136
	v_rcp_f32_e32 v136, v134
	s_nop 0
	v_mul_f32_e32 v136, v34, v136
	v_mul_f32_e32 v134, 0xbfb8aa3b, v36
	v_mul_f32_e32 v135, 0xbfb8aa3b, v37
	v_exp_f32_e32 v134, v134
	v_exp_f32_e32 v135, v135
	s_nop 0
	v_pk_add_f32 v[134:135], v[134:135], 1.0 op_sel_hi:[1,0]
	s_nop 0
	v_rcp_f32_e32 v138, v135
	s_nop 0
	v_mul_f32_e32 v135, v37, v138
	v_rcp_f32_e32 v138, v134
	s_mov_b64 s[2:3], 0xa0000
	v_mul_f32_e32 v137, v36, v138
	v_cvt_pk_bf16_f32 v134, v136, v0
	v_cvt_pk_bf16_f32 v135, v137, v135
	v_mul_f32_e32 v0, 0xbfb8aa3b, v30
	global_store_dwordx2 v[132:133], v[134:135], off offset:288
	v_exp_f32_e32 v134, v0
	v_mul_f32_e32 v0, 0xbfb8aa3b, v31
	v_exp_f32_e32 v135, v0
	v_lshl_add_u64 v[132:133], v[130:131], 0, s[2:3]
	v_pk_add_f32 v[134:135], v[134:135], 1.0 op_sel_hi:[1,0]
	s_nop 0
	v_rcp_f32_e32 v136, v135
	s_nop 0
	v_mul_f32_e32 v0, v31, v136
	v_rcp_f32_e32 v136, v134
	s_nop 0
	v_mul_f32_e32 v136, v30, v136
	v_mul_f32_e32 v134, 0xbfb8aa3b, v32
	v_mul_f32_e32 v135, 0xbfb8aa3b, v33
	v_exp_f32_e32 v134, v134
	v_exp_f32_e32 v135, v135
	s_nop 0
	v_pk_add_f32 v[134:135], v[134:135], 1.0 op_sel_hi:[1,0]
	s_nop 0
	v_rcp_f32_e32 v138, v135
	s_nop 0
	v_mul_f32_e32 v135, v33, v138
	v_rcp_f32_e32 v138, v134
	s_mov_b32 s2, 0xa0000
	v_mul_f32_e32 v137, v32, v138
	v_cvt_pk_bf16_f32 v134, v136, v0
	v_add_co_u32_e32 v136, vcc, s2, v130
	v_cvt_pk_bf16_f32 v135, v137, v135
	s_nop 0
	v_addc_co_u32_e32 v137, vcc, 0, v131, vcc
	v_mul_f32_e32 v0, 0xbfb8aa3b, v22
	global_store_dwordx2 v[136:137], v[134:135], off
	v_exp_f32_e32 v134, v0
	v_mul_f32_e32 v0, 0xbfb8aa3b, v23
	v_exp_f32_e32 v135, v0
	s_nop 0
	v_pk_add_f32 v[134:135], v[134:135], 1.0 op_sel_hi:[1,0]
	s_nop 0
	v_rcp_f32_e32 v136, v135
	s_nop 0
	v_mul_f32_e32 v0, v23, v136
	v_rcp_f32_e32 v136, v134
	s_nop 0
	v_mul_f32_e32 v136, v22, v136
	v_mul_f32_e32 v134, 0xbfb8aa3b, v24
	v_mul_f32_e32 v135, 0xbfb8aa3b, v25
	v_exp_f32_e32 v134, v134
	v_exp_f32_e32 v135, v135
	s_nop 0
	v_pk_add_f32 v[134:135], v[134:135], 1.0 op_sel_hi:[1,0]
	s_nop 0
	v_rcp_f32_e32 v138, v135
	s_nop 0
	v_mul_f32_e32 v135, v25, v138
	v_rcp_f32_e32 v138, v134
	s_nop 0
	v_mul_f32_e32 v137, v24, v138
	v_cvt_pk_bf16_f32 v134, v136, v0
	v_cvt_pk_bf16_f32 v135, v137, v135
	v_mul_f32_e32 v0, 0xbfb8aa3b, v26
	global_store_dwordx2 v[132:133], v[134:135], off offset:32
	v_exp_f32_e32 v134, v0
	v_mul_f32_e32 v0, 0xbfb8aa3b, v27
	v_exp_f32_e32 v135, v0
	s_nop 0
	v_pk_add_f32 v[134:135], v[134:135], 1.0 op_sel_hi:[1,0]
	s_nop 0
	v_rcp_f32_e32 v136, v135
	s_nop 0
	v_mul_f32_e32 v0, v27, v136
	v_rcp_f32_e32 v136, v134
	s_nop 0
	v_mul_f32_e32 v136, v26, v136
	v_mul_f32_e32 v134, 0xbfb8aa3b, v28
	v_mul_f32_e32 v135, 0xbfb8aa3b, v29
	v_exp_f32_e32 v134, v134
	v_exp_f32_e32 v135, v135
	s_nop 0
	v_pk_add_f32 v[134:135], v[134:135], 1.0 op_sel_hi:[1,0]
	s_nop 0
	v_rcp_f32_e32 v138, v135
	s_nop 0
	v_mul_f32_e32 v135, v29, v138
	v_rcp_f32_e32 v138, v134
	s_nop 0
	v_mul_f32_e32 v137, v28, v138
	v_cvt_pk_bf16_f32 v134, v136, v0
	v_cvt_pk_bf16_f32 v135, v137, v135
	v_mul_f32_e32 v0, 0xbfb8aa3b, v18
	global_store_dwordx2 v[132:133], v[134:135], off offset:256
	v_exp_f32_e32 v134, v0
	v_mul_f32_e32 v0, 0xbfb8aa3b, v19
	v_exp_f32_e32 v135, v0
	s_nop 0
	v_pk_add_f32 v[134:135], v[134:135], 1.0 op_sel_hi:[1,0]
	s_nop 0
	v_rcp_f32_e32 v136, v135
	s_nop 0
	v_mul_f32_e32 v0, v19, v136
	v_rcp_f32_e32 v136, v134
	s_nop 0
	v_mul_f32_e32 v136, v18, v136
	v_mul_f32_e32 v134, 0xbfb8aa3b, v20
	v_mul_f32_e32 v135, 0xbfb8aa3b, v21
	v_exp_f32_e32 v134, v134
	v_exp_f32_e32 v135, v135
	s_nop 0
	v_pk_add_f32 v[134:135], v[134:135], 1.0 op_sel_hi:[1,0]
	s_nop 0
	v_rcp_f32_e32 v138, v135
	s_nop 0
	v_mul_f32_e32 v135, v21, v138
	v_rcp_f32_e32 v138, v134
	s_mov_b64 s[2:3], 0xb0000
	v_mul_f32_e32 v137, v20, v138
	v_cvt_pk_bf16_f32 v134, v136, v0
	v_cvt_pk_bf16_f32 v135, v137, v135
	v_mul_f32_e32 v0, 0xbfb8aa3b, v14
	global_store_dwordx2 v[132:133], v[134:135], off offset:288
	v_exp_f32_e32 v134, v0
	v_mul_f32_e32 v0, 0xbfb8aa3b, v15
	v_exp_f32_e32 v135, v0
	v_lshl_add_u64 v[132:133], v[130:131], 0, s[2:3]
	v_pk_add_f32 v[134:135], v[134:135], 1.0 op_sel_hi:[1,0]
	s_nop 0
	v_rcp_f32_e32 v136, v135
	s_nop 0
	v_mul_f32_e32 v0, v15, v136
	v_rcp_f32_e32 v136, v134
	s_nop 0
	v_mul_f32_e32 v136, v14, v136
	v_mul_f32_e32 v134, 0xbfb8aa3b, v16
	v_mul_f32_e32 v135, 0xbfb8aa3b, v17
	v_exp_f32_e32 v134, v134
	v_exp_f32_e32 v135, v135
	s_nop 0
	v_pk_add_f32 v[134:135], v[134:135], 1.0 op_sel_hi:[1,0]
	s_nop 0
	v_rcp_f32_e32 v138, v135
	s_nop 0
	v_mul_f32_e32 v135, v17, v138
	v_rcp_f32_e32 v138, v134
	s_mov_b32 s2, 0xb0000
	v_mul_f32_e32 v137, v16, v138
	v_add_co_u32_e32 v130, vcc, s2, v130
	v_cvt_pk_bf16_f32 v134, v136, v0
	v_cvt_pk_bf16_f32 v135, v137, v135
	v_addc_co_u32_e32 v131, vcc, 0, v131, vcc
	v_mul_f32_e32 v0, 0xbfb8aa3b, v6
	global_store_dwordx2 v[130:131], v[134:135], off
	v_exp_f32_e32 v130, v0
	v_mul_f32_e32 v0, 0xbfb8aa3b, v7
	v_exp_f32_e32 v131, v0
	s_nop 0
	v_pk_add_f32 v[130:131], v[130:131], 1.0 op_sel_hi:[1,0]
	s_nop 0
	v_rcp_f32_e32 v134, v131
	s_nop 0
	v_mul_f32_e32 v0, v7, v134
	v_rcp_f32_e32 v134, v130
	s_nop 0
	v_mul_f32_e32 v134, v6, v134
	v_mul_f32_e32 v130, 0xbfb8aa3b, v8
	v_mul_f32_e32 v131, 0xbfb8aa3b, v9
	v_exp_f32_e32 v130, v130
	v_exp_f32_e32 v131, v131
	s_nop 0
	v_pk_add_f32 v[130:131], v[130:131], 1.0 op_sel_hi:[1,0]
	s_nop 0
	v_rcp_f32_e32 v136, v131
	s_nop 0
	v_mul_f32_e32 v131, v9, v136
	v_rcp_f32_e32 v136, v130
	s_nop 0
	v_mul_f32_e32 v135, v8, v136
	v_cvt_pk_bf16_f32 v130, v134, v0
	v_cvt_pk_bf16_f32 v131, v135, v131
	v_mul_f32_e32 v0, 0xbfb8aa3b, v10
	global_store_dwordx2 v[132:133], v[130:131], off offset:32
	v_exp_f32_e32 v130, v0
	v_mul_f32_e32 v0, 0xbfb8aa3b, v11
	v_exp_f32_e32 v131, v0
	s_nop 0
	v_pk_add_f32 v[130:131], v[130:131], 1.0 op_sel_hi:[1,0]
	s_nop 0
	v_rcp_f32_e32 v134, v131
	s_nop 0
	v_mul_f32_e32 v0, v11, v134
	v_rcp_f32_e32 v134, v130
	s_nop 0
	v_mul_f32_e32 v134, v10, v134
	v_mul_f32_e32 v130, 0xbfb8aa3b, v12
	v_mul_f32_e32 v131, 0xbfb8aa3b, v13
	v_exp_f32_e32 v130, v130
	v_exp_f32_e32 v131, v131
	s_nop 0
	v_pk_add_f32 v[130:131], v[130:131], 1.0 op_sel_hi:[1,0]
	s_nop 0
	v_rcp_f32_e32 v136, v131
	s_nop 0
	v_mul_f32_e32 v131, v13, v136
	v_rcp_f32_e32 v136, v130
	s_nop 0
	v_mul_f32_e32 v135, v12, v136
	v_cvt_pk_bf16_f32 v130, v134, v0
	v_cvt_pk_bf16_f32 v131, v135, v131
	v_mul_f32_e32 v0, 0xbfb8aa3b, v2
	global_store_dwordx2 v[132:133], v[130:131], off offset:256
	v_exp_f32_e32 v130, v0
	v_mul_f32_e32 v0, 0xbfb8aa3b, v3
	v_exp_f32_e32 v131, v0
	s_nop 0
	v_pk_add_f32 v[130:131], v[130:131], 1.0 op_sel_hi:[1,0]
	s_nop 0
	v_rcp_f32_e32 v134, v131
	s_nop 0
	v_mul_f32_e32 v0, v3, v134
	v_rcp_f32_e32 v134, v130
	s_nop 0
	v_mul_f32_e32 v134, v2, v134
	v_mul_f32_e32 v130, 0xbfb8aa3b, v4
	v_mul_f32_e32 v131, 0xbfb8aa3b, v5
	v_exp_f32_e32 v130, v130
	v_exp_f32_e32 v131, v131
	s_nop 0
	v_pk_add_f32 v[130:131], v[130:131], 1.0 op_sel_hi:[1,0]
	s_nop 0
	v_rcp_f32_e32 v136, v131
	s_nop 0
	v_mul_f32_e32 v131, v5, v136
	v_rcp_f32_e32 v136, v130
	s_nop 0
	v_mul_f32_e32 v135, v4, v136
	v_cvt_pk_bf16_f32 v130, v134, v0
	v_cvt_pk_bf16_f32 v131, v135, v131
	global_store_dwordx2 v[132:133], v[130:131], off offset:288

.Lswiglu_fast:
	s_lshl_b32 s4, s65, 7
	v_subrev_u32_e32 v168, s4, v162
	v_readlane_b32 s4, v253, 35
	v_readlane_b32 s5, v253, 28
	v_mov_b32_e32 v170, s4
	v_mov_b32_e32 v171, s5
	ds_read_b64 v[174:175], v170
	ds_read_b32 v171, v171
	v_lshlrev_b32_e32 v169, 2, v203
	v_sub_u32_e32 v168, v168, v169
	v_and_b32_e32 v169, 1, v203
	v_lshl_add_u32 v168, v169, 4, v168
	v_lshrrev_b32_e32 v169, 1, v203
	v_lshl_add_u32 v168, v169, 3, v168
	v_ashrrev_i32_e32 v169, 31, v168
	v_mov_b32_e32 v176, 0xbfb8aa3b
	v_mov_b32_e32 v177, 0xbfb8aa3b
	s_waitcnt lgkmcnt(0)
	v_readfirstlane_b32 s5, v171
	v_mad_i64_i32 v[172:173], s[2:3], v171, v160, 0
	v_lshl_add_u64 v[174:175], v[168:169], 1, v[174:175]
	v_lshl_add_u64 v[172:173], v[172:173], 1, v[174:175]
	s_lshl_b32 s6, s5, 5
	s_mov_b32 s7, 0
	s_mul_i32 s8, s6, 5
	s_mov_b32 s9, 0
	v_pk_mul_f32 v[206:207], v[126:127], v[176:177]
	v_exp_f32_e32 v206, v206
	v_pk_mul_f32 v[208:209], v[128:129], v[176:177]
	v_exp_f32_e32 v207, v207
	v_pk_mul_f32 v[210:211], v[118:119], v[176:177]
	v_exp_f32_e32 v208, v208
	v_pk_mul_f32 v[212:213], v[120:121], v[176:177]
	v_exp_f32_e32 v209, v209
	v_pk_mul_f32 v[214:215], v[126:127], v[122:123]
	v_exp_f32_e32 v210, v210
	v_pk_mul_f32 v[216:217], v[128:129], v[124:125]
	v_exp_f32_e32 v211, v211
	v_pk_mul_f32 v[218:219], v[118:119], v[114:115]
	v_exp_f32_e32 v212, v212
	v_pk_mul_f32 v[220:221], v[120:121], v[116:117]
	v_exp_f32_e32 v213, v213
	v_pk_add_f32 v[206:207], v[206:207], 1.0 op_sel_hi:[1,0]
	v_rcp_f32_e32 v206, v206
	v_pk_add_f32 v[208:209], v[208:209], 1.0 op_sel_hi:[1,0]
	v_rcp_f32_e32 v207, v207
	v_pk_add_f32 v[210:211], v[210:211], 1.0 op_sel_hi:[1,0]
	v_rcp_f32_e32 v208, v208
	v_pk_add_f32 v[212:213], v[212:213], 1.0 op_sel_hi:[1,0]
	v_rcp_f32_e32 v209, v209
	v_pk_mul_f32 v[214:215], v[214:215], v[206:207]
	v_rcp_f32_e32 v210, v210
	v_pk_mul_f32 v[216:217], v[216:217], v[208:209]
	v_rcp_f32_e32 v211, v211
	v_cvt_pk_bf16_f32 v222, v214, v215
	v_rcp_f32_e32 v212, v212
	v_pk_mul_f32 v[218:219], v[218:219], v[210:211]
	v_rcp_f32_e32 v213, v213
	v_cvt_pk_bf16_f32 v223, v216, v217
	v_pk_mul_f32 v[220:221], v[220:221], v[212:213]
	v_cvt_pk_bf16_f32 v224, v218, v219
	v_cvt_pk_bf16_f32 v225, v220, v221
	v_pk_mul_f32 v[226:227], v[110:111], v[176:177]
	v_exp_f32_e32 v226, v226
	v_permlane16_swap_b32_e32 v222, v224
	v_exp_f32_e32 v227, v227
	v_permlane16_swap_b32_e32 v223, v225
	global_store_dwordx4 v[172:173], v[222:225], off
	v_pk_mul_f32 v[228:229], v[112:113], v[176:177]
	v_exp_f32_e32 v228, v228
	v_lshl_add_u64 v[172:173], v[172:173], 0, s[6:7]
	v_exp_f32_e32 v229, v229
	v_pk_mul_f32 v[236:237], v[102:103], v[176:177]
	v_exp_f32_e32 v236, v236
	v_pk_mul_f32 v[238:239], v[104:105], v[176:177]
	v_exp_f32_e32 v237, v237
	v_pk_mul_f32 v[240:241], v[110:111], v[106:107]
	v_exp_f32_e32 v238, v238
	v_pk_mul_f32 v[242:243], v[112:113], v[108:109]
	v_exp_f32_e32 v239, v239
	v_pk_mul_f32 v[244:245], v[102:103], v[98:99]
	v_pk_mul_f32 v[246:247], v[104:105], v[100:101]
	v_pk_add_f32 v[226:227], v[226:227], 1.0 op_sel_hi:[1,0]
	v_rcp_f32_e32 v226, v226
	v_pk_add_f32 v[228:229], v[228:229], 1.0 op_sel_hi:[1,0]
	v_rcp_f32_e32 v227, v227
	v_pk_add_f32 v[236:237], v[236:237], 1.0 op_sel_hi:[1,0]
	v_rcp_f32_e32 v228, v228
	v_pk_add_f32 v[238:239], v[238:239], 1.0 op_sel_hi:[1,0]
	v_rcp_f32_e32 v229, v229
	v_pk_mul_f32 v[240:241], v[240:241], v[226:227]
	v_rcp_f32_e32 v236, v236
	v_pk_mul_f32 v[242:243], v[242:243], v[228:229]
	v_rcp_f32_e32 v237, v237
	v_cvt_pk_bf16_f32 v164, v240, v241
	v_rcp_f32_e32 v238, v238
	v_pk_mul_f32 v[244:245], v[244:245], v[236:237]
	v_rcp_f32_e32 v239, v239
	v_cvt_pk_bf16_f32 v165, v242, v243
	v_pk_mul_f32 v[246:247], v[246:247], v[238:239]
	v_cvt_pk_bf16_f32 v166, v244, v245
	v_cvt_pk_bf16_f32 v167, v246, v247
	v_pk_mul_f32 v[130:131], v[94:95], v[176:177]
	v_exp_f32_e32 v130, v130
	v_permlane16_swap_b32_e32 v164, v166
	v_exp_f32_e32 v131, v131
	v_permlane16_swap_b32_e32 v165, v167
	global_store_dwordx4 v[172:173], v[164:167], off
	v_pk_mul_f32 v[132:133], v[96:97], v[176:177]
	v_exp_f32_e32 v132, v132
	v_lshl_add_u64 v[172:173], v[172:173], 0, s[6:7]
	v_exp_f32_e32 v133, v133
	v_pk_mul_f32 v[134:135], v[86:87], v[176:177]
	v_exp_f32_e32 v134, v134
	v_pk_mul_f32 v[136:137], v[88:89], v[176:177]
	v_exp_f32_e32 v135, v135
	v_pk_mul_f32 v[138:139], v[94:95], v[90:91]
	v_exp_f32_e32 v136, v136
	v_pk_mul_f32 v[140:141], v[96:97], v[92:93]
	v_exp_f32_e32 v137, v137
	v_pk_mul_f32 v[142:143], v[86:87], v[82:83]
	v_pk_mul_f32 v[144:145], v[88:89], v[84:85]
	v_pk_add_f32 v[130:131], v[130:131], 1.0 op_sel_hi:[1,0]
	v_rcp_f32_e32 v130, v130
	v_pk_add_f32 v[132:133], v[132:133], 1.0 op_sel_hi:[1,0]
	v_rcp_f32_e32 v131, v131
	v_pk_add_f32 v[134:135], v[134:135], 1.0 op_sel_hi:[1,0]
	v_rcp_f32_e32 v132, v132
	v_pk_add_f32 v[136:137], v[136:137], 1.0 op_sel_hi:[1,0]
	v_rcp_f32_e32 v133, v133
	v_pk_mul_f32 v[138:139], v[138:139], v[130:131]
	v_rcp_f32_e32 v134, v134
	v_pk_mul_f32 v[140:141], v[140:141], v[132:133]
	v_rcp_f32_e32 v135, v135
	v_cvt_pk_bf16_f32 v146, v138, v139
	v_rcp_f32_e32 v136, v136
	v_pk_mul_f32 v[142:143], v[142:143], v[134:135]
	v_rcp_f32_e32 v137, v137
	v_cvt_pk_bf16_f32 v147, v140, v141
	v_pk_mul_f32 v[144:145], v[144:145], v[136:137]
	v_cvt_pk_bf16_f32 v148, v142, v143
	v_cvt_pk_bf16_f32 v149, v144, v145
	v_pk_mul_f32 v[206:207], v[78:79], v[176:177]
	v_exp_f32_e32 v206, v206
	v_permlane16_swap_b32_e32 v146, v148
	v_exp_f32_e32 v207, v207
	v_permlane16_swap_b32_e32 v147, v149
	global_store_dwordx4 v[172:173], v[146:149], off
	v_pk_mul_f32 v[208:209], v[80:81], v[176:177]
	v_exp_f32_e32 v208, v208
	v_lshl_add_u64 v[172:173], v[172:173], 0, s[6:7]
	v_exp_f32_e32 v209, v209
	v_pk_mul_f32 v[210:211], v[70:71], v[176:177]
	v_exp_f32_e32 v210, v210
	v_pk_mul_f32 v[212:213], v[72:73], v[176:177]
	v_exp_f32_e32 v211, v211
	v_pk_mul_f32 v[214:215], v[78:79], v[74:75]
	v_exp_f32_e32 v212, v212
	v_pk_mul_f32 v[216:217], v[80:81], v[76:77]
	v_exp_f32_e32 v213, v213
	v_pk_mul_f32 v[218:219], v[70:71], v[66:67]
	v_pk_mul_f32 v[220:221], v[72:73], v[68:69]
	v_pk_add_f32 v[206:207], v[206:207], 1.0 op_sel_hi:[1,0]
	v_rcp_f32_e32 v206, v206
	v_pk_add_f32 v[208:209], v[208:209], 1.0 op_sel_hi:[1,0]
	v_rcp_f32_e32 v207, v207
	v_pk_add_f32 v[210:211], v[210:211], 1.0 op_sel_hi:[1,0]
	v_rcp_f32_e32 v208, v208
	v_pk_add_f32 v[212:213], v[212:213], 1.0 op_sel_hi:[1,0]
	v_rcp_f32_e32 v209, v209
	v_pk_mul_f32 v[214:215], v[214:215], v[206:207]
	v_rcp_f32_e32 v210, v210
	v_pk_mul_f32 v[216:217], v[216:217], v[208:209]
	v_rcp_f32_e32 v211, v211
	v_cvt_pk_bf16_f32 v222, v214, v215
	v_rcp_f32_e32 v212, v212
	v_pk_mul_f32 v[218:219], v[218:219], v[210:211]
	v_rcp_f32_e32 v213, v213
	v_cvt_pk_bf16_f32 v223, v216, v217
	v_pk_mul_f32 v[220:221], v[220:221], v[212:213]
	v_cvt_pk_bf16_f32 v224, v218, v219
	v_cvt_pk_bf16_f32 v225, v220, v221
	v_pk_mul_f32 v[226:227], v[62:63], v[176:177]
	v_exp_f32_e32 v226, v226
	v_permlane16_swap_b32_e32 v222, v224
	v_exp_f32_e32 v227, v227
	v_permlane16_swap_b32_e32 v223, v225
	global_store_dwordx4 v[172:173], v[222:225], off
	v_pk_mul_f32 v[228:229], v[64:65], v[176:177]
	v_exp_f32_e32 v228, v228
	v_lshl_add_u64 v[172:173], v[172:173], 0, s[8:9]
	v_exp_f32_e32 v229, v229
	v_pk_mul_f32 v[236:237], v[54:55], v[176:177]
	v_exp_f32_e32 v236, v236
	v_pk_mul_f32 v[238:239], v[56:57], v[176:177]
	v_exp_f32_e32 v237, v237
	v_pk_mul_f32 v[240:241], v[62:63], v[58:59]
	v_exp_f32_e32 v238, v238
	v_pk_mul_f32 v[242:243], v[64:65], v[60:61]
	v_exp_f32_e32 v239, v239
	v_pk_mul_f32 v[244:245], v[54:55], v[50:51]
	v_pk_mul_f32 v[246:247], v[56:57], v[52:53]
	v_pk_add_f32 v[226:227], v[226:227], 1.0 op_sel_hi:[1,0]
	v_rcp_f32_e32 v226, v226
	v_pk_add_f32 v[228:229], v[228:229], 1.0 op_sel_hi:[1,0]
	v_rcp_f32_e32 v227, v227
	v_pk_add_f32 v[236:237], v[236:237], 1.0 op_sel_hi:[1,0]
	v_rcp_f32_e32 v228, v228
	v_pk_add_f32 v[238:239], v[238:239], 1.0 op_sel_hi:[1,0]
	v_rcp_f32_e32 v229, v229
	v_pk_mul_f32 v[240:241], v[240:241], v[226:227]
	v_rcp_f32_e32 v236, v236
	v_pk_mul_f32 v[242:243], v[242:243], v[228:229]
	v_rcp_f32_e32 v237, v237
	v_cvt_pk_bf16_f32 v164, v240, v241
	v_rcp_f32_e32 v238, v238
	v_pk_mul_f32 v[244:245], v[244:245], v[236:237]
	v_rcp_f32_e32 v239, v239
	v_cvt_pk_bf16_f32 v165, v242, v243
	v_pk_mul_f32 v[246:247], v[246:247], v[238:239]
	v_cvt_pk_bf16_f32 v166, v244, v245
	v_cvt_pk_bf16_f32 v167, v246, v247
	v_pk_mul_f32 v[130:131], v[46:47], v[176:177]
	v_exp_f32_e32 v130, v130
	v_permlane16_swap_b32_e32 v164, v166
	v_exp_f32_e32 v131, v131
	v_permlane16_swap_b32_e32 v165, v167
	global_store_dwordx4 v[172:173], v[164:167], off
	v_pk_mul_f32 v[132:133], v[48:49], v[176:177]
	v_exp_f32_e32 v132, v132
	v_lshl_add_u64 v[172:173], v[172:173], 0, s[6:7]
	v_exp_f32_e32 v133, v133
	v_pk_mul_f32 v[134:135], v[38:39], v[176:177]
	v_exp_f32_e32 v134, v134
	v_pk_mul_f32 v[136:137], v[40:41], v[176:177]
	v_exp_f32_e32 v135, v135
	v_pk_mul_f32 v[138:139], v[46:47], v[42:43]
	v_exp_f32_e32 v136, v136
	v_pk_mul_f32 v[140:141], v[48:49], v[44:45]
	v_exp_f32_e32 v137, v137
	v_pk_mul_f32 v[142:143], v[38:39], v[34:35]
	v_pk_mul_f32 v[144:145], v[40:41], v[36:37]
	v_pk_add_f32 v[130:131], v[130:131], 1.0 op_sel_hi:[1,0]
	v_rcp_f32_e32 v130, v130
	v_pk_add_f32 v[132:133], v[132:133], 1.0 op_sel_hi:[1,0]
	v_rcp_f32_e32 v131, v131
	v_pk_add_f32 v[134:135], v[134:135], 1.0 op_sel_hi:[1,0]
	v_rcp_f32_e32 v132, v132
	v_pk_add_f32 v[136:137], v[136:137], 1.0 op_sel_hi:[1,0]
	v_rcp_f32_e32 v133, v133
	v_pk_mul_f32 v[138:139], v[138:139], v[130:131]
	v_rcp_f32_e32 v134, v134
	v_pk_mul_f32 v[140:141], v[140:141], v[132:133]
	v_rcp_f32_e32 v135, v135
	v_cvt_pk_bf16_f32 v146, v138, v139
	v_rcp_f32_e32 v136, v136
	v_pk_mul_f32 v[142:143], v[142:143], v[134:135]
	v_rcp_f32_e32 v137, v137
	v_cvt_pk_bf16_f32 v147, v140, v141
	v_pk_mul_f32 v[144:145], v[144:145], v[136:137]
	v_cvt_pk_bf16_f32 v148, v142, v143
	v_cvt_pk_bf16_f32 v149, v144, v145
	v_pk_mul_f32 v[206:207], v[30:31], v[176:177]
	v_exp_f32_e32 v206, v206
	v_permlane16_swap_b32_e32 v146, v148
	v_exp_f32_e32 v207, v207
	v_permlane16_swap_b32_e32 v147, v149
	global_store_dwordx4 v[172:173], v[146:149], off
	v_pk_mul_f32 v[208:209], v[32:33], v[176:177]
	v_exp_f32_e32 v208, v208
	v_lshl_add_u64 v[172:173], v[172:173], 0, s[6:7]
	v_exp_f32_e32 v209, v209
	v_pk_mul_f32 v[210:211], v[22:23], v[176:177]
	v_exp_f32_e32 v210, v210
	v_pk_mul_f32 v[212:213], v[24:25], v[176:177]
	v_exp_f32_e32 v211, v211
	v_pk_mul_f32 v[214:215], v[30:31], v[26:27]
	v_exp_f32_e32 v212, v212
	v_pk_mul_f32 v[216:217], v[32:33], v[28:29]
	v_exp_f32_e32 v213, v213
	v_pk_mul_f32 v[218:219], v[22:23], v[18:19]
	v_pk_mul_f32 v[220:221], v[24:25], v[20:21]
	v_pk_add_f32 v[206:207], v[206:207], 1.0 op_sel_hi:[1,0]
	v_rcp_f32_e32 v206, v206
	v_pk_add_f32 v[208:209], v[208:209], 1.0 op_sel_hi:[1,0]
	v_rcp_f32_e32 v207, v207
	v_pk_add_f32 v[210:211], v[210:211], 1.0 op_sel_hi:[1,0]
	v_rcp_f32_e32 v208, v208
	v_pk_add_f32 v[212:213], v[212:213], 1.0 op_sel_hi:[1,0]
	v_rcp_f32_e32 v209, v209
	v_pk_mul_f32 v[214:215], v[214:215], v[206:207]
	v_rcp_f32_e32 v210, v210
	v_pk_mul_f32 v[216:217], v[216:217], v[208:209]
	v_rcp_f32_e32 v211, v211
	v_cvt_pk_bf16_f32 v222, v214, v215
	v_rcp_f32_e32 v212, v212
	v_pk_mul_f32 v[218:219], v[218:219], v[210:211]
	v_rcp_f32_e32 v213, v213
	v_cvt_pk_bf16_f32 v223, v216, v217
	v_pk_mul_f32 v[220:221], v[220:221], v[212:213]
	v_cvt_pk_bf16_f32 v224, v218, v219
	v_cvt_pk_bf16_f32 v225, v220, v221
	v_pk_mul_f32 v[226:227], v[14:15], v[176:177]
	v_exp_f32_e32 v226, v226
	v_permlane16_swap_b32_e32 v222, v224
	v_exp_f32_e32 v227, v227
	v_permlane16_swap_b32_e32 v223, v225
	global_store_dwordx4 v[172:173], v[222:225], off
	v_pk_mul_f32 v[228:229], v[16:17], v[176:177]
	v_exp_f32_e32 v228, v228
	v_lshl_add_u64 v[172:173], v[172:173], 0, s[6:7]
	v_exp_f32_e32 v229, v229
	v_pk_mul_f32 v[236:237], v[6:7], v[176:177]
	v_exp_f32_e32 v236, v236
	v_pk_mul_f32 v[238:239], v[8:9], v[176:177]
	v_exp_f32_e32 v237, v237
	v_pk_mul_f32 v[240:241], v[14:15], v[10:11]
	v_exp_f32_e32 v238, v238
	v_pk_mul_f32 v[242:243], v[16:17], v[12:13]
	v_exp_f32_e32 v239, v239
	v_pk_mul_f32 v[244:245], v[6:7], v[2:3]
	v_pk_mul_f32 v[246:247], v[8:9], v[4:5]
	v_pk_add_f32 v[226:227], v[226:227], 1.0 op_sel_hi:[1,0]
	v_rcp_f32_e32 v226, v226
	v_pk_add_f32 v[228:229], v[228:229], 1.0 op_sel_hi:[1,0]
	v_rcp_f32_e32 v227, v227
	v_pk_add_f32 v[236:237], v[236:237], 1.0 op_sel_hi:[1,0]
	v_rcp_f32_e32 v228, v228
	v_pk_add_f32 v[238:239], v[238:239], 1.0 op_sel_hi:[1,0]
	v_rcp_f32_e32 v229, v229
	v_pk_mul_f32 v[240:241], v[240:241], v[226:227]
	v_rcp_f32_e32 v236, v236
	v_pk_mul_f32 v[242:243], v[242:243], v[228:229]
	v_rcp_f32_e32 v237, v237
	v_cvt_pk_bf16_f32 v164, v240, v241
	v_rcp_f32_e32 v238, v238
	v_pk_mul_f32 v[244:245], v[244:245], v[236:237]
	v_rcp_f32_e32 v239, v239
	v_cvt_pk_bf16_f32 v165, v242, v243
	v_pk_mul_f32 v[246:247], v[246:247], v[238:239]
	v_cvt_pk_bf16_f32 v166, v244, v245
	v_cvt_pk_bf16_f32 v167, v246, v247
	s_nop 0
	v_permlane16_swap_b32_e32 v164, v166
	v_permlane16_swap_b32_e32 v165, v167
	global_store_dwordx4 v[172:173], v[164:167], off
	s_branch .LBB0_816
.Lglu_fast:
	s_lshl_b32 s4, s65, 7
	v_subrev_u32_e32 v168, s4, v162
	v_readlane_b32 s4, v253, 35
	v_readlane_b32 s5, v253, 28
	v_mov_b32_e32 v170, s4
	v_mov_b32_e32 v171, s5
	ds_read_b64 v[174:175], v170
	ds_read_b32 v171, v171
	v_readlane_b32 s4, v253, 44
	v_mov_b32_e32 v170, s4
	ds_read_b64 v[248:249], v170
	v_ashrrev_i32_e32 v169, 31, v168
	s_mov_b64 s[4:5], 0x1000
	s_waitcnt lgkmcnt(0)
	v_lshl_add_u64 v[248:249], v[168:169], 2, v[248:249]
	global_load_dwordx4 v[130:133], v[248:249], off
	global_load_dwordx4 v[134:137], v[248:249], off offset:64
	v_lshl_add_u64 v[248:249], v[248:249], 0, s[4:5]
	global_load_dwordx4 v[138:141], v[248:249], off
	global_load_dwordx4 v[142:145], v[248:249], off offset:64
	v_lshlrev_b32_e32 v169, 2, v203
	v_sub_u32_e32 v168, v168, v169
	v_and_b32_e32 v169, 1, v203
	v_lshl_add_u32 v168, v169, 4, v168
	v_lshrrev_b32_e32 v169, 1, v203
	v_lshl_add_u32 v168, v169, 3, v168
	v_ashrrev_i32_e32 v169, 31, v168
	v_mov_b32_e32 v176, 0xbfb8aa3b
	v_mov_b32_e32 v177, 0xbfb8aa3b
	s_waitcnt lgkmcnt(0)
	v_readfirstlane_b32 s5, v171
	v_mad_i64_i32 v[172:173], s[2:3], v171, v160, 0
	v_lshl_add_u64 v[174:175], v[168:169], 1, v[174:175]
	v_lshl_add_u64 v[172:173], v[172:173], 1, v[174:175]
	s_lshl_b32 s6, s5, 5
	s_mov_b32 s7, 0
	s_mul_i32 s8, s6, 5
	s_mov_b32 s9, 0
	s_waitcnt vmcnt(0)
	v_pk_add_f32 v[206:207], v[122:123], v[138:139]
	v_pk_add_f32 v[208:209], v[124:125], v[140:141]
	v_pk_add_f32 v[210:211], v[114:115], v[142:143]
	v_pk_add_f32 v[212:213], v[116:117], v[144:145]
	v_pk_mul_f32 v[206:207], v[206:207], v[176:177]
	v_exp_f32_e32 v206, v206
	v_pk_mul_f32 v[208:209], v[208:209], v[176:177]
	v_exp_f32_e32 v207, v207
	v_pk_mul_f32 v[210:211], v[210:211], v[176:177]
	v_exp_f32_e32 v208, v208
	v_pk_mul_f32 v[212:213], v[212:213], v[176:177]
	v_exp_f32_e32 v209, v209
	v_pk_add_f32 v[214:215], v[126:127], v[130:131]
	v_exp_f32_e32 v210, v210
	v_pk_add_f32 v[216:217], v[128:129], v[132:133]
	v_exp_f32_e32 v211, v211
	v_pk_add_f32 v[218:219], v[118:119], v[134:135]
	v_exp_f32_e32 v212, v212
	v_pk_add_f32 v[220:221], v[120:121], v[136:137]
	v_exp_f32_e32 v213, v213
	v_pk_add_f32 v[206:207], v[206:207], 1.0 op_sel_hi:[1,0]
	v_rcp_f32_e32 v206, v206
	v_pk_add_f32 v[208:209], v[208:209], 1.0 op_sel_hi:[1,0]
	v_rcp_f32_e32 v207, v207
	v_pk_add_f32 v[210:211], v[210:211], 1.0 op_sel_hi:[1,0]
	v_rcp_f32_e32 v208, v208
	v_pk_add_f32 v[212:213], v[212:213], 1.0 op_sel_hi:[1,0]
	v_rcp_f32_e32 v209, v209
	v_pk_mul_f32 v[214:215], v[214:215], v[206:207]
	v_rcp_f32_e32 v210, v210
	v_pk_mul_f32 v[216:217], v[216:217], v[208:209]
	v_rcp_f32_e32 v211, v211
	v_cvt_pk_bf16_f32 v222, v214, v215
	v_rcp_f32_e32 v212, v212
	v_pk_mul_f32 v[218:219], v[218:219], v[210:211]
	v_rcp_f32_e32 v213, v213
	v_cvt_pk_bf16_f32 v223, v216, v217
	v_pk_mul_f32 v[220:221], v[220:221], v[212:213]
	v_cvt_pk_bf16_f32 v224, v218, v219
	v_cvt_pk_bf16_f32 v225, v220, v221
	v_pk_add_f32 v[226:227], v[106:107], v[138:139]
	v_permlane16_swap_b32_e32 v222, v224
	v_permlane16_swap_b32_e32 v223, v225
	global_store_dwordx4 v[172:173], v[222:225], off
	v_pk_add_f32 v[228:229], v[108:109], v[140:141]
	v_lshl_add_u64 v[172:173], v[172:173], 0, s[6:7]
	v_pk_add_f32 v[236:237], v[98:99], v[142:143]
	v_pk_add_f32 v[238:239], v[100:101], v[144:145]
	v_pk_mul_f32 v[226:227], v[226:227], v[176:177]
	v_exp_f32_e32 v226, v226
	v_pk_mul_f32 v[228:229], v[228:229], v[176:177]
	v_exp_f32_e32 v227, v227
	v_pk_mul_f32 v[236:237], v[236:237], v[176:177]
	v_exp_f32_e32 v228, v228
	v_pk_mul_f32 v[238:239], v[238:239], v[176:177]
	v_exp_f32_e32 v229, v229
	v_pk_add_f32 v[240:241], v[110:111], v[130:131]
	v_exp_f32_e32 v236, v236
	v_pk_add_f32 v[242:243], v[112:113], v[132:133]
	v_exp_f32_e32 v237, v237
	v_pk_add_f32 v[244:245], v[102:103], v[134:135]
	v_exp_f32_e32 v238, v238
	v_pk_add_f32 v[246:247], v[104:105], v[136:137]
	v_exp_f32_e32 v239, v239
	v_pk_add_f32 v[226:227], v[226:227], 1.0 op_sel_hi:[1,0]
	v_rcp_f32_e32 v226, v226
	v_pk_add_f32 v[228:229], v[228:229], 1.0 op_sel_hi:[1,0]
	v_rcp_f32_e32 v227, v227
	v_pk_add_f32 v[236:237], v[236:237], 1.0 op_sel_hi:[1,0]
	v_rcp_f32_e32 v228, v228
	v_pk_add_f32 v[238:239], v[238:239], 1.0 op_sel_hi:[1,0]
	v_rcp_f32_e32 v229, v229
	v_pk_mul_f32 v[240:241], v[240:241], v[226:227]
	v_rcp_f32_e32 v236, v236
	v_pk_mul_f32 v[242:243], v[242:243], v[228:229]
	v_rcp_f32_e32 v237, v237
	v_cvt_pk_bf16_f32 v164, v240, v241
	v_rcp_f32_e32 v238, v238
	v_pk_mul_f32 v[244:245], v[244:245], v[236:237]
	v_rcp_f32_e32 v239, v239
	v_cvt_pk_bf16_f32 v165, v242, v243
	v_pk_mul_f32 v[246:247], v[246:247], v[238:239]
	v_cvt_pk_bf16_f32 v166, v244, v245
	v_cvt_pk_bf16_f32 v167, v246, v247
	v_pk_add_f32 v[206:207], v[90:91], v[138:139]
	v_permlane16_swap_b32_e32 v164, v166
	v_permlane16_swap_b32_e32 v165, v167
	global_store_dwordx4 v[172:173], v[164:167], off
	v_pk_add_f32 v[208:209], v[92:93], v[140:141]
	v_lshl_add_u64 v[172:173], v[172:173], 0, s[6:7]
	v_pk_add_f32 v[210:211], v[82:83], v[142:143]
	v_pk_add_f32 v[212:213], v[84:85], v[144:145]
	v_pk_mul_f32 v[206:207], v[206:207], v[176:177]
	v_exp_f32_e32 v206, v206
	v_pk_mul_f32 v[208:209], v[208:209], v[176:177]
	v_exp_f32_e32 v207, v207
	v_pk_mul_f32 v[210:211], v[210:211], v[176:177]
	v_exp_f32_e32 v208, v208
	v_pk_mul_f32 v[212:213], v[212:213], v[176:177]
	v_exp_f32_e32 v209, v209
	v_pk_add_f32 v[214:215], v[94:95], v[130:131]
	v_exp_f32_e32 v210, v210
	v_pk_add_f32 v[216:217], v[96:97], v[132:133]
	v_exp_f32_e32 v211, v211
	v_pk_add_f32 v[218:219], v[86:87], v[134:135]
	v_exp_f32_e32 v212, v212
	v_pk_add_f32 v[220:221], v[88:89], v[136:137]
	v_exp_f32_e32 v213, v213
	v_pk_add_f32 v[206:207], v[206:207], 1.0 op_sel_hi:[1,0]
	v_rcp_f32_e32 v206, v206
	v_pk_add_f32 v[208:209], v[208:209], 1.0 op_sel_hi:[1,0]
	v_rcp_f32_e32 v207, v207
	v_pk_add_f32 v[210:211], v[210:211], 1.0 op_sel_hi:[1,0]
	v_rcp_f32_e32 v208, v208
	v_pk_add_f32 v[212:213], v[212:213], 1.0 op_sel_hi:[1,0]
	v_rcp_f32_e32 v209, v209
	v_pk_mul_f32 v[214:215], v[214:215], v[206:207]
	v_rcp_f32_e32 v210, v210
	v_pk_mul_f32 v[216:217], v[216:217], v[208:209]
	v_rcp_f32_e32 v211, v211
	v_cvt_pk_bf16_f32 v222, v214, v215
	v_rcp_f32_e32 v212, v212
	v_pk_mul_f32 v[218:219], v[218:219], v[210:211]
	v_rcp_f32_e32 v213, v213
	v_cvt_pk_bf16_f32 v223, v216, v217
	v_pk_mul_f32 v[220:221], v[220:221], v[212:213]
	v_cvt_pk_bf16_f32 v224, v218, v219
	v_cvt_pk_bf16_f32 v225, v220, v221
	v_pk_add_f32 v[226:227], v[74:75], v[138:139]
	v_permlane16_swap_b32_e32 v222, v224
	v_permlane16_swap_b32_e32 v223, v225
	global_store_dwordx4 v[172:173], v[222:225], off
	v_pk_add_f32 v[228:229], v[76:77], v[140:141]
	v_lshl_add_u64 v[172:173], v[172:173], 0, s[6:7]
	v_pk_add_f32 v[236:237], v[66:67], v[142:143]
	v_pk_add_f32 v[238:239], v[68:69], v[144:145]
	v_pk_mul_f32 v[226:227], v[226:227], v[176:177]
	v_exp_f32_e32 v226, v226
	v_pk_mul_f32 v[228:229], v[228:229], v[176:177]
	v_exp_f32_e32 v227, v227
	v_pk_mul_f32 v[236:237], v[236:237], v[176:177]
	v_exp_f32_e32 v228, v228
	v_pk_mul_f32 v[238:239], v[238:239], v[176:177]
	v_exp_f32_e32 v229, v229
	v_pk_add_f32 v[240:241], v[78:79], v[130:131]
	v_exp_f32_e32 v236, v236
	v_pk_add_f32 v[242:243], v[80:81], v[132:133]
	v_exp_f32_e32 v237, v237
	v_pk_add_f32 v[244:245], v[70:71], v[134:135]
	v_exp_f32_e32 v238, v238
	v_pk_add_f32 v[246:247], v[72:73], v[136:137]
	v_exp_f32_e32 v239, v239
	v_pk_add_f32 v[226:227], v[226:227], 1.0 op_sel_hi:[1,0]
	v_rcp_f32_e32 v226, v226
	v_pk_add_f32 v[228:229], v[228:229], 1.0 op_sel_hi:[1,0]
	v_rcp_f32_e32 v227, v227
	v_pk_add_f32 v[236:237], v[236:237], 1.0 op_sel_hi:[1,0]
	v_rcp_f32_e32 v228, v228
	v_pk_add_f32 v[238:239], v[238:239], 1.0 op_sel_hi:[1,0]
	v_rcp_f32_e32 v229, v229
	v_pk_mul_f32 v[240:241], v[240:241], v[226:227]
	v_rcp_f32_e32 v236, v236
	v_pk_mul_f32 v[242:243], v[242:243], v[228:229]
	v_rcp_f32_e32 v237, v237
	v_cvt_pk_bf16_f32 v164, v240, v241
	v_rcp_f32_e32 v238, v238
	v_pk_mul_f32 v[244:245], v[244:245], v[236:237]
	v_rcp_f32_e32 v239, v239
	v_cvt_pk_bf16_f32 v165, v242, v243
	v_pk_mul_f32 v[246:247], v[246:247], v[238:239]
	v_cvt_pk_bf16_f32 v166, v244, v245
	v_cvt_pk_bf16_f32 v167, v246, v247
	v_pk_add_f32 v[206:207], v[58:59], v[138:139]
	v_permlane16_swap_b32_e32 v164, v166
	v_permlane16_swap_b32_e32 v165, v167
	global_store_dwordx4 v[172:173], v[164:167], off
	v_pk_add_f32 v[208:209], v[60:61], v[140:141]
	v_lshl_add_u64 v[172:173], v[172:173], 0, s[8:9]
	v_pk_add_f32 v[210:211], v[50:51], v[142:143]
	v_pk_add_f32 v[212:213], v[52:53], v[144:145]
	v_pk_mul_f32 v[206:207], v[206:207], v[176:177]
	v_exp_f32_e32 v206, v206
	v_pk_mul_f32 v[208:209], v[208:209], v[176:177]
	v_exp_f32_e32 v207, v207
	v_pk_mul_f32 v[210:211], v[210:211], v[176:177]
	v_exp_f32_e32 v208, v208
	v_pk_mul_f32 v[212:213], v[212:213], v[176:177]
	v_exp_f32_e32 v209, v209
	v_pk_add_f32 v[214:215], v[62:63], v[130:131]
	v_exp_f32_e32 v210, v210
	v_pk_add_f32 v[216:217], v[64:65], v[132:133]
	v_exp_f32_e32 v211, v211
	v_pk_add_f32 v[218:219], v[54:55], v[134:135]
	v_exp_f32_e32 v212, v212
	v_pk_add_f32 v[220:221], v[56:57], v[136:137]
	v_exp_f32_e32 v213, v213
	v_pk_add_f32 v[206:207], v[206:207], 1.0 op_sel_hi:[1,0]
	v_rcp_f32_e32 v206, v206
	v_pk_add_f32 v[208:209], v[208:209], 1.0 op_sel_hi:[1,0]
	v_rcp_f32_e32 v207, v207
	v_pk_add_f32 v[210:211], v[210:211], 1.0 op_sel_hi:[1,0]
	v_rcp_f32_e32 v208, v208
	v_pk_add_f32 v[212:213], v[212:213], 1.0 op_sel_hi:[1,0]
	v_rcp_f32_e32 v209, v209
	v_pk_mul_f32 v[214:215], v[214:215], v[206:207]
	v_rcp_f32_e32 v210, v210
	v_pk_mul_f32 v[216:217], v[216:217], v[208:209]
	v_rcp_f32_e32 v211, v211
	v_cvt_pk_bf16_f32 v222, v214, v215
	v_rcp_f32_e32 v212, v212
	v_pk_mul_f32 v[218:219], v[218:219], v[210:211]
	v_rcp_f32_e32 v213, v213
	v_cvt_pk_bf16_f32 v223, v216, v217
	v_pk_mul_f32 v[220:221], v[220:221], v[212:213]
	v_cvt_pk_bf16_f32 v224, v218, v219
	v_cvt_pk_bf16_f32 v225, v220, v221
	v_pk_add_f32 v[226:227], v[42:43], v[138:139]
	v_permlane16_swap_b32_e32 v222, v224
	v_permlane16_swap_b32_e32 v223, v225
	global_store_dwordx4 v[172:173], v[222:225], off
	v_pk_add_f32 v[228:229], v[44:45], v[140:141]
	v_lshl_add_u64 v[172:173], v[172:173], 0, s[6:7]
	v_pk_add_f32 v[236:237], v[34:35], v[142:143]
	v_pk_add_f32 v[238:239], v[36:37], v[144:145]
	v_pk_mul_f32 v[226:227], v[226:227], v[176:177]
	v_exp_f32_e32 v226, v226
	v_pk_mul_f32 v[228:229], v[228:229], v[176:177]
	v_exp_f32_e32 v227, v227
	v_pk_mul_f32 v[236:237], v[236:237], v[176:177]
	v_exp_f32_e32 v228, v228
	v_pk_mul_f32 v[238:239], v[238:239], v[176:177]
	v_exp_f32_e32 v229, v229
	v_pk_add_f32 v[240:241], v[46:47], v[130:131]
	v_exp_f32_e32 v236, v236
	v_pk_add_f32 v[242:243], v[48:49], v[132:133]
	v_exp_f32_e32 v237, v237
	v_pk_add_f32 v[244:245], v[38:39], v[134:135]
	v_exp_f32_e32 v238, v238
	v_pk_add_f32 v[246:247], v[40:41], v[136:137]
	v_exp_f32_e32 v239, v239
	v_pk_add_f32 v[226:227], v[226:227], 1.0 op_sel_hi:[1,0]
	v_rcp_f32_e32 v226, v226
	v_pk_add_f32 v[228:229], v[228:229], 1.0 op_sel_hi:[1,0]
	v_rcp_f32_e32 v227, v227
	v_pk_add_f32 v[236:237], v[236:237], 1.0 op_sel_hi:[1,0]
	v_rcp_f32_e32 v228, v228
	v_pk_add_f32 v[238:239], v[238:239], 1.0 op_sel_hi:[1,0]
	v_rcp_f32_e32 v229, v229
	v_pk_mul_f32 v[240:241], v[240:241], v[226:227]
	v_rcp_f32_e32 v236, v236
	v_pk_mul_f32 v[242:243], v[242:243], v[228:229]
	v_rcp_f32_e32 v237, v237
	v_cvt_pk_bf16_f32 v164, v240, v241
	v_rcp_f32_e32 v238, v238
	v_pk_mul_f32 v[244:245], v[244:245], v[236:237]
	v_rcp_f32_e32 v239, v239
	v_cvt_pk_bf16_f32 v165, v242, v243
	v_pk_mul_f32 v[246:247], v[246:247], v[238:239]
	v_cvt_pk_bf16_f32 v166, v244, v245
	v_cvt_pk_bf16_f32 v167, v246, v247
	v_pk_add_f32 v[206:207], v[26:27], v[138:139]
	v_permlane16_swap_b32_e32 v164, v166
	v_permlane16_swap_b32_e32 v165, v167
	global_store_dwordx4 v[172:173], v[164:167], off
	v_pk_add_f32 v[208:209], v[28:29], v[140:141]
	v_lshl_add_u64 v[172:173], v[172:173], 0, s[6:7]
	v_pk_add_f32 v[210:211], v[18:19], v[142:143]
	v_pk_add_f32 v[212:213], v[20:21], v[144:145]
	v_pk_mul_f32 v[206:207], v[206:207], v[176:177]
	v_exp_f32_e32 v206, v206
	v_pk_mul_f32 v[208:209], v[208:209], v[176:177]
	v_exp_f32_e32 v207, v207
	v_pk_mul_f32 v[210:211], v[210:211], v[176:177]
	v_exp_f32_e32 v208, v208
	v_pk_mul_f32 v[212:213], v[212:213], v[176:177]
	v_exp_f32_e32 v209, v209
	v_pk_add_f32 v[214:215], v[30:31], v[130:131]
	v_exp_f32_e32 v210, v210
	v_pk_add_f32 v[216:217], v[32:33], v[132:133]
	v_exp_f32_e32 v211, v211
	v_pk_add_f32 v[218:219], v[22:23], v[134:135]
	v_exp_f32_e32 v212, v212
	v_pk_add_f32 v[220:221], v[24:25], v[136:137]
	v_exp_f32_e32 v213, v213
	v_pk_add_f32 v[206:207], v[206:207], 1.0 op_sel_hi:[1,0]
	v_rcp_f32_e32 v206, v206
	v_pk_add_f32 v[208:209], v[208:209], 1.0 op_sel_hi:[1,0]
	v_rcp_f32_e32 v207, v207
	v_pk_add_f32 v[210:211], v[210:211], 1.0 op_sel_hi:[1,0]
	v_rcp_f32_e32 v208, v208
	v_pk_add_f32 v[212:213], v[212:213], 1.0 op_sel_hi:[1,0]
	v_rcp_f32_e32 v209, v209
	v_pk_mul_f32 v[214:215], v[214:215], v[206:207]
	v_rcp_f32_e32 v210, v210
	v_pk_mul_f32 v[216:217], v[216:217], v[208:209]
	v_rcp_f32_e32 v211, v211
	v_cvt_pk_bf16_f32 v222, v214, v215
	v_rcp_f32_e32 v212, v212
	v_pk_mul_f32 v[218:219], v[218:219], v[210:211]
	v_rcp_f32_e32 v213, v213
	v_cvt_pk_bf16_f32 v223, v216, v217
	v_pk_mul_f32 v[220:221], v[220:221], v[212:213]
	v_cvt_pk_bf16_f32 v224, v218, v219
	v_cvt_pk_bf16_f32 v225, v220, v221
	v_pk_add_f32 v[226:227], v[10:11], v[138:139]
	v_permlane16_swap_b32_e32 v222, v224
	v_permlane16_swap_b32_e32 v223, v225
	global_store_dwordx4 v[172:173], v[222:225], off
	v_pk_add_f32 v[228:229], v[12:13], v[140:141]
	v_lshl_add_u64 v[172:173], v[172:173], 0, s[6:7]
	v_pk_add_f32 v[236:237], v[2:3], v[142:143]
	v_pk_add_f32 v[238:239], v[4:5], v[144:145]
	v_pk_mul_f32 v[226:227], v[226:227], v[176:177]
	v_exp_f32_e32 v226, v226
	v_pk_mul_f32 v[228:229], v[228:229], v[176:177]
	v_exp_f32_e32 v227, v227
	v_pk_mul_f32 v[236:237], v[236:237], v[176:177]
	v_exp_f32_e32 v228, v228
	v_pk_mul_f32 v[238:239], v[238:239], v[176:177]
	v_exp_f32_e32 v229, v229
	v_pk_add_f32 v[240:241], v[14:15], v[130:131]
	v_exp_f32_e32 v236, v236
	v_pk_add_f32 v[242:243], v[16:17], v[132:133]
	v_exp_f32_e32 v237, v237
	v_pk_add_f32 v[244:245], v[6:7], v[134:135]
	v_exp_f32_e32 v238, v238
	v_pk_add_f32 v[246:247], v[8:9], v[136:137]
	v_exp_f32_e32 v239, v239
	v_pk_add_f32 v[226:227], v[226:227], 1.0 op_sel_hi:[1,0]
	v_rcp_f32_e32 v226, v226
	v_pk_add_f32 v[228:229], v[228:229], 1.0 op_sel_hi:[1,0]
	v_rcp_f32_e32 v227, v227
	v_pk_add_f32 v[236:237], v[236:237], 1.0 op_sel_hi:[1,0]
	v_rcp_f32_e32 v228, v228
	v_pk_add_f32 v[238:239], v[238:239], 1.0 op_sel_hi:[1,0]
	v_rcp_f32_e32 v229, v229
	v_pk_mul_f32 v[240:241], v[240:241], v[226:227]
	v_rcp_f32_e32 v236, v236
	v_pk_mul_f32 v[242:243], v[242:243], v[228:229]
	v_rcp_f32_e32 v237, v237
	v_cvt_pk_bf16_f32 v164, v240, v241
	v_rcp_f32_e32 v238, v238
	v_pk_mul_f32 v[244:245], v[244:245], v[236:237]
	v_rcp_f32_e32 v239, v239
	v_cvt_pk_bf16_f32 v165, v242, v243
	v_pk_mul_f32 v[246:247], v[246:247], v[238:239]
	v_cvt_pk_bf16_f32 v166, v244, v245
	v_cvt_pk_bf16_f32 v167, v246, v247
	s_nop 0
	v_permlane16_swap_b32_e32 v164, v166
	v_permlane16_swap_b32_e32 v165, v167
	global_store_dwordx4 v[172:173], v[164:167], off
	s_branch .LBB0_816
.Lretg_fast:
	v_add_u32_e32 v168, 0xfffffc00, v162
	v_readlane_b32 s4, v253, 36
	v_mov_b32_e32 v170, s4
	ds_read_b64 v[174:175], v170
	v_lshlrev_b32_e32 v169, 2, v203
	v_sub_u32_e32 v168, v168, v169
	v_and_b32_e32 v169, 1, v203
	v_lshl_add_u32 v168, v169, 4, v168
	v_lshrrev_b32_e32 v169, 1, v203
	v_lshl_add_u32 v168, v169, 3, v168
	v_ashrrev_i32_e32 v169, 31, v168
	v_ashrrev_i32_e32 v161, 31, v160
	v_mov_b32_e32 v176, 0xbfb8aa3b
	v_mov_b32_e32 v177, 0xbfb8aa3b
	v_lshlrev_b64 v[172:173], 12, v[160:161]
	s_waitcnt lgkmcnt(0)
	v_lshl_add_u64 v[174:175], v[168:169], 1, v[174:175]
	v_lshl_add_u64 v[172:173], v[172:173], 0, v[174:175]
	s_mov_b64 s[6:7], 0x10000
	s_mov_b64 s[8:9], 0x50000
	v_pk_mul_f32 v[206:207], v[126:127], v[176:177]
	v_exp_f32_e32 v206, v206
	v_pk_mul_f32 v[208:209], v[128:129], v[176:177]
	v_exp_f32_e32 v207, v207
	v_pk_mul_f32 v[210:211], v[118:119], v[176:177]
	v_exp_f32_e32 v208, v208
	v_pk_mul_f32 v[212:213], v[120:121], v[176:177]
	v_exp_f32_e32 v209, v209
	v_pk_add_f32 v[206:207], v[206:207], 1.0 op_sel_hi:[1,0]
	v_exp_f32_e32 v210, v210
	v_pk_add_f32 v[208:209], v[208:209], 1.0 op_sel_hi:[1,0]
	v_exp_f32_e32 v211, v211
	v_pk_mul_f32 v[226:227], v[122:123], v[176:177]
	v_exp_f32_e32 v212, v212
	v_pk_add_f32 v[210:211], v[210:211], 1.0 op_sel_hi:[1,0]
	v_exp_f32_e32 v213, v213
	v_pk_mul_f32 v[228:229], v[124:125], v[176:177]
	v_rcp_f32_e32 v206, v206
	v_pk_add_f32 v[212:213], v[212:213], 1.0 op_sel_hi:[1,0]
	v_rcp_f32_e32 v207, v207
	v_pk_mul_f32 v[236:237], v[114:115], v[176:177]
	v_rcp_f32_e32 v208, v208
	v_pk_mul_f32 v[214:215], v[126:127], v[206:207]
	v_rcp_f32_e32 v209, v209
	v_cvt_pk_bf16_f32 v222, v214, v215
	v_rcp_f32_e32 v210, v210
	v_pk_mul_f32 v[216:217], v[128:129], v[208:209]
	v_rcp_f32_e32 v211, v211
	v_cvt_pk_bf16_f32 v223, v216, v217
	v_rcp_f32_e32 v212, v212
	v_pk_mul_f32 v[218:219], v[118:119], v[210:211]
	v_rcp_f32_e32 v213, v213
	v_cvt_pk_bf16_f32 v224, v218, v219
	v_exp_f32_e32 v226, v226
	v_pk_mul_f32 v[220:221], v[120:121], v[212:213]
	v_exp_f32_e32 v227, v227
	v_cvt_pk_bf16_f32 v225, v220, v221
	v_exp_f32_e32 v228, v228
	v_permlane16_swap_b32_e32 v222, v224
	v_exp_f32_e32 v229, v229
	v_permlane16_swap_b32_e32 v223, v225
	v_exp_f32_e32 v236, v236
	global_store_dwordx4 v[172:173], v[222:225], off
	v_exp_f32_e32 v237, v237
	v_pk_mul_f32 v[238:239], v[116:117], v[176:177]
	v_exp_f32_e32 v238, v238
	v_pk_add_f32 v[226:227], v[226:227], 1.0 op_sel_hi:[1,0]
	v_exp_f32_e32 v239, v239
	v_pk_add_f32 v[228:229], v[228:229], 1.0 op_sel_hi:[1,0]
	v_rcp_f32_e32 v226, v226
	v_pk_add_f32 v[236:237], v[236:237], 1.0 op_sel_hi:[1,0]
	v_rcp_f32_e32 v227, v227
	v_pk_add_f32 v[238:239], v[238:239], 1.0 op_sel_hi:[1,0]
	v_rcp_f32_e32 v228, v228
	v_pk_mul_f32 v[240:241], v[122:123], v[226:227]
	v_rcp_f32_e32 v229, v229
	v_cvt_pk_bf16_f32 v164, v240, v241
	v_rcp_f32_e32 v236, v236
	v_pk_mul_f32 v[242:243], v[124:125], v[228:229]
	v_rcp_f32_e32 v237, v237
	v_cvt_pk_bf16_f32 v165, v242, v243
	v_rcp_f32_e32 v238, v238
	v_pk_mul_f32 v[244:245], v[114:115], v[236:237]
	v_rcp_f32_e32 v239, v239
	v_cvt_pk_bf16_f32 v166, v244, v245
	v_pk_mul_f32 v[246:247], v[116:117], v[238:239]
	v_cvt_pk_bf16_f32 v167, v246, v247
	v_permlane16_swap_b32_e32 v164, v166
	v_pk_mul_f32 v[130:131], v[110:111], v[176:177]
	v_exp_f32_e32 v130, v130
	v_permlane16_swap_b32_e32 v165, v167
	v_exp_f32_e32 v131, v131
	global_store_dwordx4 v[172:173], v[164:167], off offset:256
	v_pk_mul_f32 v[132:133], v[112:113], v[176:177]
	v_exp_f32_e32 v132, v132
	v_lshl_add_u64 v[172:173], v[172:173], 0, s[6:7]
	v_exp_f32_e32 v133, v133
	v_pk_mul_f32 v[134:135], v[102:103], v[176:177]
	v_exp_f32_e32 v134, v134
	v_pk_mul_f32 v[136:137], v[104:105], v[176:177]
	v_exp_f32_e32 v135, v135
	v_pk_add_f32 v[130:131], v[130:131], 1.0 op_sel_hi:[1,0]
	v_exp_f32_e32 v136, v136
	v_pk_add_f32 v[132:133], v[132:133], 1.0 op_sel_hi:[1,0]
	v_exp_f32_e32 v137, v137
	v_pk_add_f32 v[134:135], v[134:135], 1.0 op_sel_hi:[1,0]
	v_rcp_f32_e32 v130, v130
	v_pk_add_f32 v[136:137], v[136:137], 1.0 op_sel_hi:[1,0]
	v_rcp_f32_e32 v131, v131
	v_pk_mul_f32 v[206:207], v[106:107], v[176:177]
	v_rcp_f32_e32 v132, v132
	v_pk_mul_f32 v[138:139], v[110:111], v[130:131]
	v_rcp_f32_e32 v133, v133
	v_cvt_pk_bf16_f32 v146, v138, v139
	v_rcp_f32_e32 v134, v134
	v_pk_mul_f32 v[140:141], v[112:113], v[132:133]
	v_rcp_f32_e32 v135, v135
	v_cvt_pk_bf16_f32 v147, v140, v141
	v_rcp_f32_e32 v136, v136
	v_pk_mul_f32 v[142:143], v[102:103], v[134:135]
	v_rcp_f32_e32 v137, v137
	v_cvt_pk_bf16_f32 v148, v142, v143
	v_exp_f32_e32 v206, v206
	v_pk_mul_f32 v[144:145], v[104:105], v[136:137]
	v_exp_f32_e32 v207, v207
	v_cvt_pk_bf16_f32 v149, v144, v145
	v_permlane16_swap_b32_e32 v146, v148
	v_pk_mul_f32 v[208:209], v[108:109], v[176:177]
	v_exp_f32_e32 v208, v208
	v_permlane16_swap_b32_e32 v147, v149
	v_exp_f32_e32 v209, v209
	global_store_dwordx4 v[172:173], v[146:149], off
	v_pk_mul_f32 v[210:211], v[98:99], v[176:177]
	v_exp_f32_e32 v210, v210
	v_pk_mul_f32 v[212:213], v[100:101], v[176:177]
	v_exp_f32_e32 v211, v211
	v_pk_add_f32 v[206:207], v[206:207], 1.0 op_sel_hi:[1,0]
	v_exp_f32_e32 v212, v212
	v_pk_add_f32 v[208:209], v[208:209], 1.0 op_sel_hi:[1,0]
	v_exp_f32_e32 v213, v213
	v_pk_add_f32 v[210:211], v[210:211], 1.0 op_sel_hi:[1,0]
	v_rcp_f32_e32 v206, v206
	v_pk_add_f32 v[212:213], v[212:213], 1.0 op_sel_hi:[1,0]
	v_rcp_f32_e32 v207, v207
	v_pk_mul_f32 v[226:227], v[94:95], v[176:177]
	v_rcp_f32_e32 v208, v208
	v_pk_mul_f32 v[214:215], v[106:107], v[206:207]
	v_rcp_f32_e32 v209, v209
	v_cvt_pk_bf16_f32 v222, v214, v215
	v_rcp_f32_e32 v210, v210
	v_pk_mul_f32 v[216:217], v[108:109], v[208:209]
	v_rcp_f32_e32 v211, v211
	v_cvt_pk_bf16_f32 v223, v216, v217
	v_rcp_f32_e32 v212, v212
	v_pk_mul_f32 v[218:219], v[98:99], v[210:211]
	v_rcp_f32_e32 v213, v213
	v_cvt_pk_bf16_f32 v224, v218, v219
	v_exp_f32_e32 v226, v226
	v_pk_mul_f32 v[220:221], v[100:101], v[212:213]
	v_exp_f32_e32 v227, v227
	v_cvt_pk_bf16_f32 v225, v220, v221
	v_permlane16_swap_b32_e32 v222, v224
	v_pk_mul_f32 v[228:229], v[96:97], v[176:177]
	v_exp_f32_e32 v228, v228
	v_permlane16_swap_b32_e32 v223, v225
	v_exp_f32_e32 v229, v229
	global_store_dwordx4 v[172:173], v[222:225], off offset:256
	v_pk_mul_f32 v[236:237], v[86:87], v[176:177]
	v_exp_f32_e32 v236, v236
	v_lshl_add_u64 v[172:173], v[172:173], 0, s[6:7]
	v_exp_f32_e32 v237, v237
	v_pk_mul_f32 v[238:239], v[88:89], v[176:177]
	v_exp_f32_e32 v238, v238
	v_pk_add_f32 v[226:227], v[226:227], 1.0 op_sel_hi:[1,0]
	v_exp_f32_e32 v239, v239
	v_pk_add_f32 v[228:229], v[228:229], 1.0 op_sel_hi:[1,0]
	v_rcp_f32_e32 v226, v226
	v_pk_add_f32 v[236:237], v[236:237], 1.0 op_sel_hi:[1,0]
	v_rcp_f32_e32 v227, v227
	v_pk_add_f32 v[238:239], v[238:239], 1.0 op_sel_hi:[1,0]
	v_rcp_f32_e32 v228, v228
	v_pk_mul_f32 v[240:241], v[94:95], v[226:227]
	v_rcp_f32_e32 v229, v229
	v_cvt_pk_bf16_f32 v164, v240, v241
	v_rcp_f32_e32 v236, v236
	v_pk_mul_f32 v[242:243], v[96:97], v[228:229]
	v_rcp_f32_e32 v237, v237
	v_cvt_pk_bf16_f32 v165, v242, v243
	v_rcp_f32_e32 v238, v238
	v_pk_mul_f32 v[244:245], v[86:87], v[236:237]
	v_rcp_f32_e32 v239, v239
	v_cvt_pk_bf16_f32 v166, v244, v245
	v_pk_mul_f32 v[246:247], v[88:89], v[238:239]
	v_cvt_pk_bf16_f32 v167, v246, v247
	v_permlane16_swap_b32_e32 v164, v166
	v_pk_mul_f32 v[130:131], v[90:91], v[176:177]
	v_exp_f32_e32 v130, v130
	v_permlane16_swap_b32_e32 v165, v167
	v_exp_f32_e32 v131, v131
	global_store_dwordx4 v[172:173], v[164:167], off
	v_pk_mul_f32 v[132:133], v[92:93], v[176:177]
	v_exp_f32_e32 v132, v132
	v_pk_mul_f32 v[134:135], v[82:83], v[176:177]
	v_exp_f32_e32 v133, v133
	v_pk_mul_f32 v[136:137], v[84:85], v[176:177]
	v_exp_f32_e32 v134, v134
	v_pk_add_f32 v[130:131], v[130:131], 1.0 op_sel_hi:[1,0]
	v_exp_f32_e32 v135, v135
	v_pk_add_f32 v[132:133], v[132:133], 1.0 op_sel_hi:[1,0]
	v_exp_f32_e32 v136, v136
	v_pk_add_f32 v[134:135], v[134:135], 1.0 op_sel_hi:[1,0]
	v_exp_f32_e32 v137, v137
	v_pk_mul_f32 v[206:207], v[78:79], v[176:177]
	v_rcp_f32_e32 v130, v130
	v_pk_add_f32 v[136:137], v[136:137], 1.0 op_sel_hi:[1,0]
	v_rcp_f32_e32 v131, v131
	v_pk_mul_f32 v[208:209], v[80:81], v[176:177]
	v_rcp_f32_e32 v132, v132
	v_pk_mul_f32 v[138:139], v[90:91], v[130:131]
	v_rcp_f32_e32 v133, v133
	v_cvt_pk_bf16_f32 v146, v138, v139
	v_rcp_f32_e32 v134, v134
	v_pk_mul_f32 v[140:141], v[92:93], v[132:133]
	v_rcp_f32_e32 v135, v135
	v_cvt_pk_bf16_f32 v147, v140, v141
	v_rcp_f32_e32 v136, v136
	v_pk_mul_f32 v[142:143], v[82:83], v[134:135]
	v_rcp_f32_e32 v137, v137
	v_cvt_pk_bf16_f32 v148, v142, v143
	v_exp_f32_e32 v206, v206
	v_pk_mul_f32 v[144:145], v[84:85], v[136:137]
	v_exp_f32_e32 v207, v207
	v_cvt_pk_bf16_f32 v149, v144, v145
	v_exp_f32_e32 v208, v208
	v_permlane16_swap_b32_e32 v146, v148
	v_exp_f32_e32 v209, v209
	v_permlane16_swap_b32_e32 v147, v149
	global_store_dwordx4 v[172:173], v[146:149], off offset:256
	v_pk_mul_f32 v[210:211], v[70:71], v[176:177]
	v_exp_f32_e32 v210, v210
	v_lshl_add_u64 v[172:173], v[172:173], 0, s[6:7]
	v_exp_f32_e32 v211, v211
	v_pk_mul_f32 v[212:213], v[72:73], v[176:177]
	v_exp_f32_e32 v212, v212
	v_pk_add_f32 v[206:207], v[206:207], 1.0 op_sel_hi:[1,0]
	v_exp_f32_e32 v213, v213
	v_pk_add_f32 v[208:209], v[208:209], 1.0 op_sel_hi:[1,0]
	v_rcp_f32_e32 v206, v206
	v_pk_add_f32 v[210:211], v[210:211], 1.0 op_sel_hi:[1,0]
	v_rcp_f32_e32 v207, v207
	v_pk_add_f32 v[212:213], v[212:213], 1.0 op_sel_hi:[1,0]
	v_rcp_f32_e32 v208, v208
	v_pk_mul_f32 v[214:215], v[78:79], v[206:207]
	v_rcp_f32_e32 v209, v209
	v_cvt_pk_bf16_f32 v222, v214, v215
	v_rcp_f32_e32 v210, v210
	v_pk_mul_f32 v[216:217], v[80:81], v[208:209]
	v_rcp_f32_e32 v211, v211
	v_cvt_pk_bf16_f32 v223, v216, v217
	v_rcp_f32_e32 v212, v212
	v_pk_mul_f32 v[218:219], v[70:71], v[210:211]
	v_rcp_f32_e32 v213, v213
	v_cvt_pk_bf16_f32 v224, v218, v219
	v_pk_mul_f32 v[220:221], v[72:73], v[212:213]
	v_cvt_pk_bf16_f32 v225, v220, v221
	v_permlane16_swap_b32_e32 v222, v224
	v_pk_mul_f32 v[226:227], v[74:75], v[176:177]
	v_exp_f32_e32 v226, v226
	v_permlane16_swap_b32_e32 v223, v225
	v_exp_f32_e32 v227, v227
	global_store_dwordx4 v[172:173], v[222:225], off
	v_pk_mul_f32 v[228:229], v[76:77], v[176:177]
	v_exp_f32_e32 v228, v228
	v_pk_mul_f32 v[236:237], v[66:67], v[176:177]
	v_exp_f32_e32 v229, v229
	v_pk_mul_f32 v[238:239], v[68:69], v[176:177]
	v_exp_f32_e32 v236, v236
	v_pk_add_f32 v[226:227], v[226:227], 1.0 op_sel_hi:[1,0]
	v_exp_f32_e32 v237, v237
	v_pk_add_f32 v[228:229], v[228:229], 1.0 op_sel_hi:[1,0]
	v_exp_f32_e32 v238, v238
	v_pk_add_f32 v[236:237], v[236:237], 1.0 op_sel_hi:[1,0]
	v_exp_f32_e32 v239, v239
	v_pk_mul_f32 v[130:131], v[62:63], v[176:177]
	v_rcp_f32_e32 v226, v226
	v_pk_add_f32 v[238:239], v[238:239], 1.0 op_sel_hi:[1,0]
	v_rcp_f32_e32 v227, v227
	v_pk_mul_f32 v[132:133], v[64:65], v[176:177]
	v_rcp_f32_e32 v228, v228
	v_pk_mul_f32 v[240:241], v[74:75], v[226:227]
	v_rcp_f32_e32 v229, v229
	v_cvt_pk_bf16_f32 v164, v240, v241
	v_rcp_f32_e32 v236, v236
	v_pk_mul_f32 v[242:243], v[76:77], v[228:229]
	v_rcp_f32_e32 v237, v237
	v_cvt_pk_bf16_f32 v165, v242, v243
	v_rcp_f32_e32 v238, v238
	v_pk_mul_f32 v[244:245], v[66:67], v[236:237]
	v_rcp_f32_e32 v239, v239
	v_cvt_pk_bf16_f32 v166, v244, v245
	v_exp_f32_e32 v130, v130
	v_pk_mul_f32 v[246:247], v[68:69], v[238:239]
	v_exp_f32_e32 v131, v131
	v_cvt_pk_bf16_f32 v167, v246, v247
	v_exp_f32_e32 v132, v132
	v_permlane16_swap_b32_e32 v164, v166
	v_exp_f32_e32 v133, v133
	v_permlane16_swap_b32_e32 v165, v167
	global_store_dwordx4 v[172:173], v[164:167], off offset:256
	v_pk_mul_f32 v[134:135], v[54:55], v[176:177]
	v_exp_f32_e32 v134, v134
	v_lshl_add_u64 v[172:173], v[172:173], 0, s[8:9]
	v_exp_f32_e32 v135, v135
	v_pk_mul_f32 v[136:137], v[56:57], v[176:177]
	v_exp_f32_e32 v136, v136
	v_pk_add_f32 v[130:131], v[130:131], 1.0 op_sel_hi:[1,0]
	v_exp_f32_e32 v137, v137
	v_pk_add_f32 v[132:133], v[132:133], 1.0 op_sel_hi:[1,0]
	v_rcp_f32_e32 v130, v130
	v_pk_add_f32 v[134:135], v[134:135], 1.0 op_sel_hi:[1,0]
	v_rcp_f32_e32 v131, v131
	v_pk_add_f32 v[136:137], v[136:137], 1.0 op_sel_hi:[1,0]
	v_rcp_f32_e32 v132, v132
	v_pk_mul_f32 v[138:139], v[62:63], v[130:131]
	v_rcp_f32_e32 v133, v133
	v_cvt_pk_bf16_f32 v146, v138, v139
	v_rcp_f32_e32 v134, v134
	v_pk_mul_f32 v[140:141], v[64:65], v[132:133]
	v_rcp_f32_e32 v135, v135
	v_cvt_pk_bf16_f32 v147, v140, v141
	v_rcp_f32_e32 v136, v136
	v_pk_mul_f32 v[142:143], v[54:55], v[134:135]
	v_rcp_f32_e32 v137, v137
	v_cvt_pk_bf16_f32 v148, v142, v143
	v_pk_mul_f32 v[144:145], v[56:57], v[136:137]
	v_cvt_pk_bf16_f32 v149, v144, v145
	v_permlane16_swap_b32_e32 v146, v148
	v_pk_mul_f32 v[206:207], v[58:59], v[176:177]
	v_exp_f32_e32 v206, v206
	v_permlane16_swap_b32_e32 v147, v149
	v_exp_f32_e32 v207, v207
	global_store_dwordx4 v[172:173], v[146:149], off
	v_pk_mul_f32 v[208:209], v[60:61], v[176:177]
	v_exp_f32_e32 v208, v208
	v_pk_mul_f32 v[210:211], v[50:51], v[176:177]
	v_exp_f32_e32 v209, v209
	v_pk_mul_f32 v[212:213], v[52:53], v[176:177]
	v_exp_f32_e32 v210, v210
	v_pk_add_f32 v[206:207], v[206:207], 1.0 op_sel_hi:[1,0]
	v_exp_f32_e32 v211, v211
	v_pk_add_f32 v[208:209], v[208:209], 1.0 op_sel_hi:[1,0]
	v_exp_f32_e32 v212, v212
	v_pk_add_f32 v[210:211], v[210:211], 1.0 op_sel_hi:[1,0]
	v_exp_f32_e32 v213, v213
	v_pk_mul_f32 v[226:227], v[46:47], v[176:177]
	v_rcp_f32_e32 v206, v206
	v_pk_add_f32 v[212:213], v[212:213], 1.0 op_sel_hi:[1,0]
	v_rcp_f32_e32 v207, v207
	v_pk_mul_f32 v[228:229], v[48:49], v[176:177]
	v_rcp_f32_e32 v208, v208
	v_pk_mul_f32 v[214:215], v[58:59], v[206:207]
	v_rcp_f32_e32 v209, v209
	v_cvt_pk_bf16_f32 v222, v214, v215
	v_rcp_f32_e32 v210, v210
	v_pk_mul_f32 v[216:217], v[60:61], v[208:209]
	v_rcp_f32_e32 v211, v211
	v_cvt_pk_bf16_f32 v223, v216, v217
	v_rcp_f32_e32 v212, v212
	v_pk_mul_f32 v[218:219], v[50:51], v[210:211]
	v_rcp_f32_e32 v213, v213
	v_cvt_pk_bf16_f32 v224, v218, v219
	v_exp_f32_e32 v226, v226
	v_pk_mul_f32 v[220:221], v[52:53], v[212:213]
	v_exp_f32_e32 v227, v227
	v_cvt_pk_bf16_f32 v225, v220, v221
	v_exp_f32_e32 v228, v228
	v_permlane16_swap_b32_e32 v222, v224
	v_exp_f32_e32 v229, v229
	v_permlane16_swap_b32_e32 v223, v225
	global_store_dwordx4 v[172:173], v[222:225], off offset:256
	v_pk_mul_f32 v[236:237], v[38:39], v[176:177]
	v_exp_f32_e32 v236, v236
	v_lshl_add_u64 v[172:173], v[172:173], 0, s[6:7]
	v_exp_f32_e32 v237, v237
	v_pk_mul_f32 v[238:239], v[40:41], v[176:177]
	v_exp_f32_e32 v238, v238
	v_pk_add_f32 v[226:227], v[226:227], 1.0 op_sel_hi:[1,0]
	v_exp_f32_e32 v239, v239
	v_pk_add_f32 v[228:229], v[228:229], 1.0 op_sel_hi:[1,0]
	v_rcp_f32_e32 v226, v226
	v_pk_add_f32 v[236:237], v[236:237], 1.0 op_sel_hi:[1,0]
	v_rcp_f32_e32 v227, v227
	v_pk_add_f32 v[238:239], v[238:239], 1.0 op_sel_hi:[1,0]
	v_rcp_f32_e32 v228, v228
	v_pk_mul_f32 v[240:241], v[46:47], v[226:227]
	v_rcp_f32_e32 v229, v229
	v_cvt_pk_bf16_f32 v164, v240, v241
	v_rcp_f32_e32 v236, v236
	v_pk_mul_f32 v[242:243], v[48:49], v[228:229]
	v_rcp_f32_e32 v237, v237
	v_cvt_pk_bf16_f32 v165, v242, v243
	v_rcp_f32_e32 v238, v238
	v_pk_mul_f32 v[244:245], v[38:39], v[236:237]
	v_rcp_f32_e32 v239, v239
	v_cvt_pk_bf16_f32 v166, v244, v245
	v_pk_mul_f32 v[246:247], v[40:41], v[238:239]
	v_cvt_pk_bf16_f32 v167, v246, v247
	v_permlane16_swap_b32_e32 v164, v166
	v_pk_mul_f32 v[130:131], v[42:43], v[176:177]
	v_exp_f32_e32 v130, v130
	v_permlane16_swap_b32_e32 v165, v167
	v_exp_f32_e32 v131, v131
	global_store_dwordx4 v[172:173], v[164:167], off
	v_pk_mul_f32 v[132:133], v[44:45], v[176:177]
	v_exp_f32_e32 v132, v132
	v_pk_mul_f32 v[134:135], v[34:35], v[176:177]
	v_exp_f32_e32 v133, v133
	v_pk_mul_f32 v[136:137], v[36:37], v[176:177]
	v_exp_f32_e32 v134, v134
	v_pk_add_f32 v[130:131], v[130:131], 1.0 op_sel_hi:[1,0]
	v_exp_f32_e32 v135, v135
	v_pk_add_f32 v[132:133], v[132:133], 1.0 op_sel_hi:[1,0]
	v_exp_f32_e32 v136, v136
	v_pk_add_f32 v[134:135], v[134:135], 1.0 op_sel_hi:[1,0]
	v_exp_f32_e32 v137, v137
	v_pk_mul_f32 v[206:207], v[30:31], v[176:177]
	v_rcp_f32_e32 v130, v130
	v_pk_add_f32 v[136:137], v[136:137], 1.0 op_sel_hi:[1,0]
	v_rcp_f32_e32 v131, v131
	v_pk_mul_f32 v[208:209], v[32:33], v[176:177]
	v_rcp_f32_e32 v132, v132
	v_pk_mul_f32 v[138:139], v[42:43], v[130:131]
	v_rcp_f32_e32 v133, v133
	v_cvt_pk_bf16_f32 v146, v138, v139
	v_rcp_f32_e32 v134, v134
	v_pk_mul_f32 v[140:141], v[44:45], v[132:133]
	v_rcp_f32_e32 v135, v135
	v_cvt_pk_bf16_f32 v147, v140, v141
	v_rcp_f32_e32 v136, v136
	v_pk_mul_f32 v[142:143], v[34:35], v[134:135]
	v_rcp_f32_e32 v137, v137
	v_cvt_pk_bf16_f32 v148, v142, v143
	v_exp_f32_e32 v206, v206
	v_pk_mul_f32 v[144:145], v[36:37], v[136:137]
	v_exp_f32_e32 v207, v207
	v_cvt_pk_bf16_f32 v149, v144, v145
	v_exp_f32_e32 v208, v208
	v_permlane16_swap_b32_e32 v146, v148
	v_exp_f32_e32 v209, v209
	v_permlane16_swap_b32_e32 v147, v149
	global_store_dwordx4 v[172:173], v[146:149], off offset:256
	v_pk_mul_f32 v[210:211], v[22:23], v[176:177]
	v_exp_f32_e32 v210, v210
	v_lshl_add_u64 v[172:173], v[172:173], 0, s[6:7]
	v_exp_f32_e32 v211, v211
	v_pk_mul_f32 v[212:213], v[24:25], v[176:177]
	v_exp_f32_e32 v212, v212
	v_pk_add_f32 v[206:207], v[206:207], 1.0 op_sel_hi:[1,0]
	v_exp_f32_e32 v213, v213
	v_pk_add_f32 v[208:209], v[208:209], 1.0 op_sel_hi:[1,0]
	v_rcp_f32_e32 v206, v206
	v_pk_add_f32 v[210:211], v[210:211], 1.0 op_sel_hi:[1,0]
	v_rcp_f32_e32 v207, v207
	v_pk_add_f32 v[212:213], v[212:213], 1.0 op_sel_hi:[1,0]
	v_rcp_f32_e32 v208, v208
	v_pk_mul_f32 v[214:215], v[30:31], v[206:207]
	v_rcp_f32_e32 v209, v209
	v_cvt_pk_bf16_f32 v222, v214, v215
	v_rcp_f32_e32 v210, v210
	v_pk_mul_f32 v[216:217], v[32:33], v[208:209]
	v_rcp_f32_e32 v211, v211
	v_cvt_pk_bf16_f32 v223, v216, v217
	v_rcp_f32_e32 v212, v212
	v_pk_mul_f32 v[218:219], v[22:23], v[210:211]
	v_rcp_f32_e32 v213, v213
	v_cvt_pk_bf16_f32 v224, v218, v219
	v_pk_mul_f32 v[220:221], v[24:25], v[212:213]
	v_cvt_pk_bf16_f32 v225, v220, v221
	v_permlane16_swap_b32_e32 v222, v224
	v_pk_mul_f32 v[226:227], v[26:27], v[176:177]
	v_exp_f32_e32 v226, v226
	v_permlane16_swap_b32_e32 v223, v225
	v_exp_f32_e32 v227, v227
	global_store_dwordx4 v[172:173], v[222:225], off
	v_pk_mul_f32 v[228:229], v[28:29], v[176:177]
	v_exp_f32_e32 v228, v228
	v_pk_mul_f32 v[236:237], v[18:19], v[176:177]
	v_exp_f32_e32 v229, v229
	v_pk_mul_f32 v[238:239], v[20:21], v[176:177]
	v_exp_f32_e32 v236, v236
	v_pk_add_f32 v[226:227], v[226:227], 1.0 op_sel_hi:[1,0]
	v_exp_f32_e32 v237, v237
	v_pk_add_f32 v[228:229], v[228:229], 1.0 op_sel_hi:[1,0]
	v_exp_f32_e32 v238, v238
	v_pk_add_f32 v[236:237], v[236:237], 1.0 op_sel_hi:[1,0]
	v_exp_f32_e32 v239, v239
	v_pk_mul_f32 v[130:131], v[14:15], v[176:177]
	v_rcp_f32_e32 v226, v226
	v_pk_add_f32 v[238:239], v[238:239], 1.0 op_sel_hi:[1,0]
	v_rcp_f32_e32 v227, v227
	v_pk_mul_f32 v[132:133], v[16:17], v[176:177]
	v_rcp_f32_e32 v228, v228
	v_pk_mul_f32 v[240:241], v[26:27], v[226:227]
	v_rcp_f32_e32 v229, v229
	v_cvt_pk_bf16_f32 v164, v240, v241
	v_rcp_f32_e32 v236, v236
	v_pk_mul_f32 v[242:243], v[28:29], v[228:229]
	v_rcp_f32_e32 v237, v237
	v_cvt_pk_bf16_f32 v165, v242, v243
	v_rcp_f32_e32 v238, v238
	v_pk_mul_f32 v[244:245], v[18:19], v[236:237]
	v_rcp_f32_e32 v239, v239
	v_cvt_pk_bf16_f32 v166, v244, v245
	v_exp_f32_e32 v130, v130
	v_pk_mul_f32 v[246:247], v[20:21], v[238:239]
	v_exp_f32_e32 v131, v131
	v_cvt_pk_bf16_f32 v167, v246, v247
	v_exp_f32_e32 v132, v132
	v_permlane16_swap_b32_e32 v164, v166
	v_exp_f32_e32 v133, v133
	v_permlane16_swap_b32_e32 v165, v167
	global_store_dwordx4 v[172:173], v[164:167], off offset:256
	v_pk_mul_f32 v[134:135], v[6:7], v[176:177]
	v_exp_f32_e32 v134, v134
	v_lshl_add_u64 v[172:173], v[172:173], 0, s[6:7]
	v_exp_f32_e32 v135, v135
	v_pk_mul_f32 v[136:137], v[8:9], v[176:177]
	v_exp_f32_e32 v136, v136
	v_pk_add_f32 v[130:131], v[130:131], 1.0 op_sel_hi:[1,0]
	v_exp_f32_e32 v137, v137
	v_pk_add_f32 v[132:133], v[132:133], 1.0 op_sel_hi:[1,0]
	v_rcp_f32_e32 v130, v130
	v_pk_add_f32 v[134:135], v[134:135], 1.0 op_sel_hi:[1,0]
	v_rcp_f32_e32 v131, v131
	v_pk_add_f32 v[136:137], v[136:137], 1.0 op_sel_hi:[1,0]
	v_rcp_f32_e32 v132, v132
	v_pk_mul_f32 v[138:139], v[14:15], v[130:131]
	v_rcp_f32_e32 v133, v133
	v_cvt_pk_bf16_f32 v146, v138, v139
	v_rcp_f32_e32 v134, v134
	v_pk_mul_f32 v[140:141], v[16:17], v[132:133]
	v_rcp_f32_e32 v135, v135
	v_cvt_pk_bf16_f32 v147, v140, v141
	v_rcp_f32_e32 v136, v136
	v_pk_mul_f32 v[142:143], v[6:7], v[134:135]
	v_rcp_f32_e32 v137, v137
	v_cvt_pk_bf16_f32 v148, v142, v143
	v_pk_mul_f32 v[144:145], v[8:9], v[136:137]
	v_cvt_pk_bf16_f32 v149, v144, v145
	v_permlane16_swap_b32_e32 v146, v148
	v_pk_mul_f32 v[206:207], v[10:11], v[176:177]
	v_exp_f32_e32 v206, v206
	v_permlane16_swap_b32_e32 v147, v149
	v_exp_f32_e32 v207, v207
	global_store_dwordx4 v[172:173], v[146:149], off
	v_pk_mul_f32 v[208:209], v[12:13], v[176:177]
	v_exp_f32_e32 v208, v208
	v_pk_mul_f32 v[210:211], v[2:3], v[176:177]
	v_exp_f32_e32 v209, v209
	v_pk_mul_f32 v[212:213], v[4:5], v[176:177]
	v_exp_f32_e32 v210, v210
	v_pk_add_f32 v[206:207], v[206:207], 1.0 op_sel_hi:[1,0]
	v_exp_f32_e32 v211, v211
	v_pk_add_f32 v[208:209], v[208:209], 1.0 op_sel_hi:[1,0]
	v_exp_f32_e32 v212, v212
	v_pk_add_f32 v[210:211], v[210:211], 1.0 op_sel_hi:[1,0]
	v_exp_f32_e32 v213, v213
	v_rcp_f32_e32 v206, v206
	v_pk_add_f32 v[212:213], v[212:213], 1.0 op_sel_hi:[1,0]
	v_rcp_f32_e32 v207, v207
	v_rcp_f32_e32 v208, v208
	v_pk_mul_f32 v[214:215], v[10:11], v[206:207]
	v_rcp_f32_e32 v209, v209
	v_cvt_pk_bf16_f32 v222, v214, v215
	v_rcp_f32_e32 v210, v210
	v_pk_mul_f32 v[216:217], v[12:13], v[208:209]
	v_rcp_f32_e32 v211, v211
	v_cvt_pk_bf16_f32 v223, v216, v217
	v_rcp_f32_e32 v212, v212
	v_pk_mul_f32 v[218:219], v[2:3], v[210:211]
	v_rcp_f32_e32 v213, v213
	v_cvt_pk_bf16_f32 v224, v218, v219
	v_pk_mul_f32 v[220:221], v[4:5], v[212:213]
	v_cvt_pk_bf16_f32 v225, v220, v221
	v_permlane16_swap_b32_e32 v222, v224
	s_nop 0
	v_permlane16_swap_b32_e32 v223, v225
	global_store_dwordx4 v[172:173], v[222:225], off offset:256
	s_branch .LBB0_816
.LBB0_1037:
	s_cmp_lg_u32 s21, 0
	s_cbranch_scc1 .Lswiglu_fast
	s_cbranch_scc0 .Lglu_fast
	s_cselect_b64 s[2:3], -1, 0
	s_lshl_b32 s4, s65, 7
	v_subrev_u32_e32 v146, s4, v162
	v_readlane_b32 s4, v253, 35
	v_ashrrev_i32_e32 v147, 31, v146
	v_mov_b32_e32 v138, 0
	v_mov_b32_e32 v132, s4
	v_readlane_b32 s4, v253, 44
	s_and_b64 vcc, exec, s[2:3]
	v_mov_b32_e32 v139, v138
	v_mov_b32_e32 v0, s4
	ds_read_b64 v[130:131], v0
	v_readlane_b32 s4, v253, 28
	v_mov_b32_e32 v140, v138
	v_mov_b32_e32 v141, v138
	v_mov_b32_e32 v0, s4
	ds_read_b32 v0, v0
	ds_read_b64 v[148:149], v132
	s_waitcnt lgkmcnt(0)
	v_lshl_add_u64 v[130:131], v[146:147], 2, v[130:131]
	s_mov_b64 s[4:5], 0x1000
	v_lshl_add_u64 v[134:135], v[130:131], 0, s[4:5]
	v_mov_b32_e32 v142, v138
	v_mov_b32_e32 v143, v138
	v_mov_b32_e32 v144, v138
	v_mov_b32_e32 v145, v138
	s_cbranch_vccnz .LBB0_1039
	global_load_dwordx4 v[142:145], v[130:131], off
	global_load_dwordx4 v[138:141], v[134:135], off
